# baseline (speedup 1.0000x reference)
; #define SCHED() __builtin_amdgcn_sched_barrier(0)
; #define LGKM(n) asm volatile("s_waitcnt lgkmcnt(%0)" ::"n"(n) : "memory")
; #define STAGE_A(b, h, kt) STAGE_AX(Ag, b, h, kt)
; #define STAGE_B(b, h, kt) STAGE_BX(Bg, b, h, kt)
; #define LDA(b, h) do { const unsigned pa_ = lds0 + SLOTA(b, h) + wr * 8192 + laneoff; _Pragma("unroll") for (int m = 0; m < 4; ++m)   \
;       _Pragma("unroll") for (int k = 0; k < 2; ++k) DSR(At[m][k], pa_, m * 2048 + k * 1024); } while (0)
; #define LDB(dst, b, h) do { const unsigned pb_ = lds0 + SLOTB(b, h) + wc * 4096 + laneoff; _Pragma("unroll") for (int n = 0; n < 2; ++n) \
;       _Pragma("unroll") for (int k = 0; k < 2; ++k) DSR(dst[n][k], pb_, n * 2048 + k * 1024); } while (0)
; #define BAR __builtin_amdgcn_s_barrier()
; #define LGKM(n) asm volatile("s_waitcnt lgkmcnt(%0)" ::"n"(n) : "memory")
; template <int EPI, bool SWP> ...
;     ...
;     LDB(B0, 0, 0); LDA(0, 0); STAGE_A(1, 1, t + 1);
;     LGKM(8); BAR; LGKM(0); SCHED(); MMA(0, 0, B0); BAR; SCHED();
;     LDB(B1, 0, 1); STAGE_B(0, 0, t + 2);
;     BAR; LGKM(0); SCHED(); MMA(0, 1, B1); BAR; SCHED();
;     LDA(0, 1); STAGE_A(0, 0, t + 2);
;     BAR; LGKM(0); SCHED(); MMA(1, 0, B0); BAR; SCHED();
.LBB0_123:
	ds_read_b128 v[130:133], v201 offset:0
	ds_read_b128 v[134:137], v201 offset:0x400
	ds_read_b128 v[138:141], v201 offset:0x800
	ds_read_b128 v[142:145], v201 offset:0xc00
	ds_read_b128 v[146:149], v202 offset:0
	ds_read_b128 v[150:153], v202 offset:0x400
	ds_read_b128 v[154:157], v202 offset:0x800
	ds_read_b128 v[158:161], v202 offset:0xc00
	ds_read_b128 v[162:165], v202 offset:0x1000
	ds_read_b128 v[166:169], v202 offset:0x1400
	ds_read_b128 v[170:173], v202 offset:0x1800
	v_lshl_add_u64 v[190:191], s[58:59], 0, v[194:195]
	s_mov_b64 s[70:71], 0xf260080
	s_add_i32 s74, s3, 0xc000
	ds_read_b128 v[174:177], v202 offset:0x1c00
	s_mov_b32 m0, s74
	s_mov_b64 s[70:71], 0xf310080
	s_add_u32 s94, s58, 0xf260080
	s_addc_u32 s95, s59, 0
	global_load_lds_dwordx4 v194, s[94:95]
	s_mov_b32 m0, s61
	s_nop 0
	s_add_u32 s94, s58, 0xf310080
	s_addc_u32 s95, s59, 0
	global_load_lds_dwordx4 v194, s[94:95]
	s_waitcnt lgkmcnt(8)
	s_barrier
	s_waitcnt lgkmcnt(0)
	v_mfma_f32_16x16x32_bf16 v[124:127], v[130:133], v[146:149], v[124:127]
	v_mfma_f32_16x16x32_bf16 v[120:123], v[138:141], v[146:149], v[120:123]
	v_mfma_f32_16x16x32_bf16 v[116:119], v[130:133], v[154:157], v[116:119]
	v_mfma_f32_16x16x32_bf16 v[112:115], v[138:141], v[154:157], v[112:115]
	v_mfma_f32_16x16x32_bf16 v[108:111], v[130:133], v[162:165], v[108:111]
	v_mfma_f32_16x16x32_bf16 v[104:107], v[138:141], v[162:165], v[104:107]
	v_mfma_f32_16x16x32_bf16 v[100:103], v[130:133], v[170:173], v[100:103]
	v_mfma_f32_16x16x32_bf16 v[96:99], v[138:141], v[170:173], v[96:99]
	v_mfma_f32_16x16x32_bf16 v[124:127], v[134:137], v[150:153], v[124:127]
	v_mfma_f32_16x16x32_bf16 v[120:123], v[142:145], v[150:153], v[120:123]
	v_mfma_f32_16x16x32_bf16 v[116:119], v[134:137], v[158:161], v[116:119]
	v_mfma_f32_16x16x32_bf16 v[112:115], v[142:145], v[158:161], v[112:115]
	v_mfma_f32_16x16x32_bf16 v[108:111], v[134:137], v[166:169], v[108:111]
	v_mfma_f32_16x16x32_bf16 v[104:107], v[142:145], v[166:169], v[104:107]
	v_mfma_f32_16x16x32_bf16 v[100:103], v[134:137], v[174:177], v[100:103]
	v_mfma_f32_16x16x32_bf16 v[96:99], v[142:145], v[174:177], v[96:99]
	s_barrier
	ds_read_b128 v[178:181], v203 offset:0
	ds_read_b128 v[182:185], v203 offset:0x400
	ds_read_b128 v[186:189], v203 offset:0x800
	v_lshl_add_u64 v[220:221], s[10:11], 0, v[194:195]
	s_mov_b64 s[70:71], 0x32d00100
	s_mov_b32 m0, s17
	ds_read_b128 v[196:199], v203 offset:0xc00
	s_mov_b64 s[70:71], 0x32db0100
	s_add_u32 s94, s10, 0x32d00100
	s_addc_u32 s95, s11, 0
	global_load_lds_dwordx4 v194, s[94:95]
	s_mov_b32 m0, s18
	s_nop 0
	s_add_u32 s94, s10, 0x32db0100
	s_addc_u32 s95, s11, 0
	global_load_lds_dwordx4 v194, s[94:95]
	s_barrier
	s_waitcnt lgkmcnt(0)
	v_mfma_f32_16x16x32_bf16 v[92:95], v[178:181], v[146:149], v[92:95]
	v_mfma_f32_16x16x32_bf16 v[88:91], v[186:189], v[146:149], v[88:91]
	v_mfma_f32_16x16x32_bf16 v[84:87], v[178:181], v[154:157], v[84:87]
	v_mfma_f32_16x16x32_bf16 v[80:83], v[186:189], v[154:157], v[80:83]
	v_mfma_f32_16x16x32_bf16 v[76:79], v[178:181], v[162:165], v[76:79]
	v_mfma_f32_16x16x32_bf16 v[72:75], v[186:189], v[162:165], v[72:75]
	v_mfma_f32_16x16x32_bf16 v[68:71], v[178:181], v[170:173], v[68:71]
	v_mfma_f32_16x16x32_bf16 v[64:67], v[186:189], v[170:173], v[64:67]
	v_mfma_f32_16x16x32_bf16 v[92:95], v[182:185], v[150:153], v[92:95]
	v_mfma_f32_16x16x32_bf16 v[88:91], v[196:199], v[150:153], v[88:91]
	v_mfma_f32_16x16x32_bf16 v[84:87], v[182:185], v[158:161], v[84:87]
	v_mfma_f32_16x16x32_bf16 v[80:83], v[196:199], v[158:161], v[80:83]
	v_mfma_f32_16x16x32_bf16 v[76:79], v[182:185], v[166:169], v[76:79]
	v_mfma_f32_16x16x32_bf16 v[72:75], v[196:199], v[166:169], v[72:75]
	v_mfma_f32_16x16x32_bf16 v[68:71], v[182:185], v[174:177], v[68:71]
	v_mfma_f32_16x16x32_bf16 v[64:67], v[196:199], v[174:177], v[64:67]
	s_barrier
	ds_read_b128 v[146:149], v204 offset:0
	ds_read_b128 v[150:153], v204 offset:0x400
	ds_read_b128 v[154:157], v204 offset:0x800
	ds_read_b128 v[158:161], v204 offset:0xc00
	ds_read_b128 v[162:165], v204 offset:0x1000
	ds_read_b128 v[166:169], v204 offset:0x1400
	ds_read_b128 v[170:173], v204 offset:0x1800
	s_mov_b64 s[70:71], 0xf100100
	s_mov_b32 m0, s3
	ds_read_b128 v[174:177], v204 offset:0x1c00
	s_mov_b64 s[70:71], 0xf1b0100
	s_add_u32 s94, s58, 0xf100100
	s_addc_u32 s95, s59, 0
	global_load_lds_dwordx4 v194, s[94:95]
	s_mov_b32 m0, s19
	s_nop 0
	s_add_u32 s94, s58, 0xf1b0100
	s_addc_u32 s95, s59, 0
	global_load_lds_dwordx4 v194, s[94:95]
	s_barrier
	s_waitcnt lgkmcnt(0)
	v_mfma_f32_16x16x32_bf16 v[60:63], v[130:133], v[146:149], v[60:63]
	v_mfma_f32_16x16x32_bf16 v[56:59], v[138:141], v[146:149], v[56:59]
	v_mfma_f32_16x16x32_bf16 v[52:55], v[130:133], v[154:157], v[52:55]
	v_mfma_f32_16x16x32_bf16 v[48:51], v[138:141], v[154:157], v[48:51]
	v_mfma_f32_16x16x32_bf16 v[44:47], v[130:133], v[162:165], v[44:47]
	v_mfma_f32_16x16x32_bf16 v[40:43], v[138:141], v[162:165], v[40:43]
	v_mfma_f32_16x16x32_bf16 v[36:39], v[130:133], v[170:173], v[36:39]
	v_mfma_f32_16x16x32_bf16 v[32:35], v[138:141], v[170:173], v[32:35]
	v_mfma_f32_16x16x32_bf16 v[60:63], v[134:137], v[150:153], v[60:63]
	v_mfma_f32_16x16x32_bf16 v[56:59], v[142:145], v[150:153], v[56:59]
	v_mfma_f32_16x16x32_bf16 v[52:55], v[134:137], v[158:161], v[52:55]
	v_mfma_f32_16x16x32_bf16 v[48:51], v[142:145], v[158:161], v[48:51]
	v_mfma_f32_16x16x32_bf16 v[44:47], v[134:137], v[166:169], v[44:47]
	v_mfma_f32_16x16x32_bf16 v[40:43], v[142:145], v[166:169], v[40:43]
	v_mfma_f32_16x16x32_bf16 v[36:39], v[134:137], v[174:177], v[36:39]
	v_mfma_f32_16x16x32_bf16 v[32:35], v[142:145], v[174:177], v[32:35]
	s_barrier
; #define WAIT_V(n) asm volatile("s_waitcnt vmcnt(%0)" ::"n"(n) : "memory")
; #define SCHED() __builtin_amdgcn_sched_barrier(0)
; #define LGKM(n) asm volatile("s_waitcnt lgkmcnt(%0)" ::"n"(n) : "memory")
; #define STAGE_A(b, h, kt) STAGE_AX(Ag, b, h, kt)
; #define STAGE_B(b, h, kt) STAGE_BX(Bg, b, h, kt)
; #define LDA(b, h) do { const unsigned pa_ = lds0 + SLOTA(b, h) + wr * 8192 + laneoff; _Pragma("unroll") for (int m = 0; m < 4; ++m)   \
;       _Pragma("unroll") for (int k = 0; k < 2; ++k) DSR(At[m][k], pa_, m * 2048 + k * 1024); } while (0)
; #define LDB(dst, b, h) do { const unsigned pb_ = lds0 + SLOTB(b, h) + wc * 4096 + laneoff; _Pragma("unroll") for (int n = 0; n < 2; ++n) \
;       _Pragma("unroll") for (int k = 0; k < 2; ++k) DSR(dst[n][k], pb_, n * 2048 + k * 1024); } while (0)
; #define BAR __builtin_amdgcn_s_barrier()
; #define LGKM(n) asm volatile("s_waitcnt lgkmcnt(%0)" ::"n"(n) : "memory")
; template <int EPI, bool SWP> ...
;     ...
;     STAGE_B(0, 1, t + 2);
;     WAIT_V(6); BAR; SCHED(); MMA(1, 1, B1); BAR; SCHED();
;     LDB(B0, 1, 0); LDA(1, 0); STAGE_A(0, 1, t + 2);
;     LGKM(8); BAR; LGKM(0); SCHED(); MMA(0, 0, B0); BAR; SCHED();
;     LDB(B1, 1, 1); STAGE_B(1, 0, t + 3);
;     BAR; LGKM(0); SCHED(); MMA(0, 1, B1); BAR; SCHED();
;     LDA(1, 1); STAGE_A(1, 0, t + 3);
	s_mov_b64 s[70:71], 0x32e60100
	s_add_i32 s69, s3, 0x14000
	s_mov_b32 m0, s69
	s_mov_b64 s[70:71], 0x32f10100
	s_add_u32 s94, s10, 0x32e60100
	s_addc_u32 s95, s11, 0
	global_load_lds_dwordx4 v194, s[94:95]
	s_mov_b32 m0, s30
	s_nop 0
	s_add_u32 s94, s10, 0x32f10100
	s_addc_u32 s95, s11, 0
	global_load_lds_dwordx4 v194, s[94:95]
	s_waitcnt vmcnt(6)
	s_barrier
	v_mfma_f32_16x16x32_bf16 v[28:31], v[178:181], v[146:149], v[28:31]
	v_mfma_f32_16x16x32_bf16 v[24:27], v[186:189], v[146:149], v[24:27]
	v_mfma_f32_16x16x32_bf16 v[20:23], v[178:181], v[154:157], v[20:23]
	v_mfma_f32_16x16x32_bf16 v[16:19], v[186:189], v[154:157], v[16:19]
	v_mfma_f32_16x16x32_bf16 v[12:15], v[178:181], v[162:165], v[12:15]
	v_mfma_f32_16x16x32_bf16 v[8:11], v[186:189], v[162:165], v[8:11]
	v_mfma_f32_16x16x32_bf16 v[4:7], v[178:181], v[170:173], v[4:7]
	v_mfma_f32_16x16x32_bf16 v[0:3], v[186:189], v[170:173], v[0:3]
	v_mfma_f32_16x16x32_bf16 v[28:31], v[182:185], v[150:153], v[28:31]
	v_mfma_f32_16x16x32_bf16 v[24:27], v[196:199], v[150:153], v[24:27]
	v_mfma_f32_16x16x32_bf16 v[20:23], v[182:185], v[158:161], v[20:23]
	v_mfma_f32_16x16x32_bf16 v[16:19], v[196:199], v[158:161], v[16:19]
	v_mfma_f32_16x16x32_bf16 v[12:15], v[182:185], v[166:169], v[12:15]
	v_mfma_f32_16x16x32_bf16 v[8:11], v[196:199], v[166:169], v[8:11]
	v_mfma_f32_16x16x32_bf16 v[4:7], v[182:185], v[174:177], v[4:7]
	v_mfma_f32_16x16x32_bf16 v[0:3], v[196:199], v[174:177], v[0:3]
	s_barrier
	ds_read_b128 v[130:133], v205 offset:0
	ds_read_b128 v[134:137], v205 offset:0x400
	ds_read_b128 v[138:141], v205 offset:0x800
	ds_read_b128 v[142:145], v205 offset:0xc00
	ds_read_b128 v[146:149], v206 offset:0
	ds_read_b128 v[150:153], v206 offset:0x400
	ds_read_b128 v[154:157], v206 offset:0x800
	ds_read_b128 v[158:161], v206 offset:0xc00
	ds_read_b128 v[162:165], v206 offset:0x1000
	ds_read_b128 v[166:169], v206 offset:0x1400
	s_mov_b64 s[70:71], 0xf260100
	ds_read_b128 v[170:173], v206 offset:0x1800
	s_add_i32 s71, s3, 0x4000
	ds_read_b128 v[174:177], v206 offset:0x1c00
	s_mov_b32 m0, s71
	s_mov_b64 s[72:73], 0xf310100
	s_add_u32 s94, s58, 0xf260100
	s_addc_u32 s95, s59, 0
	global_load_lds_dwordx4 v194, s[94:95]
	s_mov_b32 m0, s31
	s_nop 0
	s_add_u32 s94, s58, 0xf310100
	s_addc_u32 s95, s59, 0
	global_load_lds_dwordx4 v194, s[94:95]
	s_waitcnt lgkmcnt(8)
	s_barrier
	s_waitcnt lgkmcnt(0)
	v_mfma_f32_16x16x32_bf16 v[124:127], v[130:133], v[146:149], v[124:127]
	v_mfma_f32_16x16x32_bf16 v[120:123], v[138:141], v[146:149], v[120:123]
	v_mfma_f32_16x16x32_bf16 v[116:119], v[130:133], v[154:157], v[116:119]
	v_mfma_f32_16x16x32_bf16 v[112:115], v[138:141], v[154:157], v[112:115]
	v_mfma_f32_16x16x32_bf16 v[108:111], v[130:133], v[162:165], v[108:111]
	v_mfma_f32_16x16x32_bf16 v[104:107], v[138:141], v[162:165], v[104:107]
	v_mfma_f32_16x16x32_bf16 v[100:103], v[130:133], v[170:173], v[100:103]
	v_mfma_f32_16x16x32_bf16 v[96:99], v[138:141], v[170:173], v[96:99]
	v_mfma_f32_16x16x32_bf16 v[124:127], v[134:137], v[150:153], v[124:127]
	v_mfma_f32_16x16x32_bf16 v[120:123], v[142:145], v[150:153], v[120:123]
	v_mfma_f32_16x16x32_bf16 v[116:119], v[134:137], v[158:161], v[116:119]
	v_mfma_f32_16x16x32_bf16 v[112:115], v[142:145], v[158:161], v[112:115]
	v_mfma_f32_16x16x32_bf16 v[108:111], v[134:137], v[166:169], v[108:111]
	v_mfma_f32_16x16x32_bf16 v[104:107], v[142:145], v[166:169], v[104:107]
	v_mfma_f32_16x16x32_bf16 v[100:103], v[134:137], v[174:177], v[100:103]
	v_mfma_f32_16x16x32_bf16 v[96:99], v[142:145], v[174:177], v[96:99]
	s_barrier
	ds_read_b128 v[178:181], v207 offset:0
	ds_read_b128 v[182:185], v207 offset:0x400
	ds_read_b128 v[186:189], v207 offset:0x800
	s_mov_b64 s[72:73], 0x32d00180
	s_add_i32 s70, s3, 0x18000
	ds_read_b128 v[196:199], v207 offset:0xc00
	s_mov_b32 m0, s70
	s_mov_b64 s[72:73], 0x32db0180
	s_add_u32 s94, s10, 0x32d00180
	s_addc_u32 s95, s11, 0
	global_load_lds_dwordx4 v194, s[94:95]
	s_mov_b32 m0, s50
	s_nop 0
	s_add_u32 s94, s10, 0x32db0180
	s_addc_u32 s95, s11, 0
	global_load_lds_dwordx4 v194, s[94:95]
	s_barrier
	s_waitcnt lgkmcnt(0)
	v_mfma_f32_16x16x32_bf16 v[92:95], v[178:181], v[146:149], v[92:95]
	v_mfma_f32_16x16x32_bf16 v[88:91], v[186:189], v[146:149], v[88:91]
	v_mfma_f32_16x16x32_bf16 v[84:87], v[178:181], v[154:157], v[84:87]
	v_mfma_f32_16x16x32_bf16 v[80:83], v[186:189], v[154:157], v[80:83]
	v_mfma_f32_16x16x32_bf16 v[76:79], v[178:181], v[162:165], v[76:79]
	v_mfma_f32_16x16x32_bf16 v[72:75], v[186:189], v[162:165], v[72:75]
	v_mfma_f32_16x16x32_bf16 v[68:71], v[178:181], v[170:173], v[68:71]
	v_mfma_f32_16x16x32_bf16 v[64:67], v[186:189], v[170:173], v[64:67]
	v_mfma_f32_16x16x32_bf16 v[92:95], v[182:185], v[150:153], v[92:95]
	v_mfma_f32_16x16x32_bf16 v[88:91], v[196:199], v[150:153], v[88:91]
	v_mfma_f32_16x16x32_bf16 v[84:87], v[182:185], v[158:161], v[84:87]
	v_mfma_f32_16x16x32_bf16 v[80:83], v[196:199], v[158:161], v[80:83]
	v_mfma_f32_16x16x32_bf16 v[76:79], v[182:185], v[166:169], v[76:79]
	v_mfma_f32_16x16x32_bf16 v[72:75], v[196:199], v[166:169], v[72:75]
	v_mfma_f32_16x16x32_bf16 v[68:71], v[182:185], v[174:177], v[68:71]
	v_mfma_f32_16x16x32_bf16 v[64:67], v[196:199], v[174:177], v[64:67]
	s_barrier
	ds_read_b128 v[146:149], v208 offset:0
	ds_read_b128 v[150:153], v208 offset:0x400
	ds_read_b128 v[154:157], v208 offset:0x800
	ds_read_b128 v[158:161], v208 offset:0xc00
	ds_read_b128 v[162:165], v208 offset:0x1000
	ds_read_b128 v[166:169], v208 offset:0x1400
	s_mov_b64 s[72:73], 0xf100180
	ds_read_b128 v[170:173], v208 offset:0x1800
	s_add_i32 s72, s3, 0x8000
	ds_read_b128 v[174:177], v208 offset:0x1c00
	s_mov_b32 m0, s72
	s_mov_b64 s[76:77], 0xf1b0180
	s_add_u32 s94, s58, 0xf100180
	s_addc_u32 s95, s59, 0
	global_load_lds_dwordx4 v194, s[94:95]
	v_lshl_add_u64 v[190:191], v[190:191], 0, s[76:77]
	s_mov_b32 m0, s51
	s_nop 0
	s_add_u32 s94, s58, 0xf1b0180
	s_addc_u32 s95, s59, 0
	global_load_lds_dwordx4 v194, s[94:95]
	s_barrier
; #define WAIT_V(n) asm volatile("s_waitcnt vmcnt(%0)" ::"n"(n) : "memory")
; #define SCHED() __builtin_amdgcn_sched_barrier(0)
; #define LGKM(n) asm volatile("s_waitcnt lgkmcnt(%0)" ::"n"(n) : "memory")
; #define STAGE_A(b, h, kt) STAGE_AX(Ag, b, h, kt)
; #define STAGE_B(b, h, kt) STAGE_BX(Bg, b, h, kt)
; #define LDA(b, h) do { const unsigned pa_ = lds0 + SLOTA(b, h) + wr * 8192 + laneoff; _Pragma("unroll") for (int m = 0; m < 4; ++m)   \
;       _Pragma("unroll") for (int k = 0; k < 2; ++k) DSR(At[m][k], pa_, m * 2048 + k * 1024); } while (0)
; #define LDB(dst, b, h) do { const unsigned pb_ = lds0 + SLOTB(b, h) + wc * 4096 + laneoff; _Pragma("unroll") for (int n = 0; n < 2; ++n) \
;       _Pragma("unroll") for (int k = 0; k < 2; ++k) DSR(dst[n][k], pb_, n * 2048 + k * 1024); } while (0)
; #define BAR __builtin_amdgcn_s_barrier()
; #define LGKM(n) asm volatile("s_waitcnt lgkmcnt(%0)" ::"n"(n) : "memory")
; template <int EPI, bool SWP> ...
;     ...
;     BAR; LGKM(0); SCHED(); MMA(1, 0, B0); BAR; SCHED();
;     STAGE_B(1, 1, t + 3);
;     WAIT_V(6); BAR; SCHED(); MMA(1, 1, B1); BAR; SCHED();
;   }
;   { LDB(B0, 0, 0); LDA(0, 0); STAGE_A(1, 1, nt - 1);
;     BAR; LGKM(0); SCHED(); MMA(0, 0, B0); BAR; SCHED();
;     LDB(B1, 0, 1); BAR; LGKM(0); SCHED(); MMA(0, 1, B1); BAR; SCHED();
	s_waitcnt lgkmcnt(0)
	v_mfma_f32_16x16x32_bf16 v[60:63], v[130:133], v[146:149], v[60:63]
	v_mfma_f32_16x16x32_bf16 v[56:59], v[138:141], v[146:149], v[56:59]
	v_mfma_f32_16x16x32_bf16 v[52:55], v[130:133], v[154:157], v[52:55]
	v_mfma_f32_16x16x32_bf16 v[48:51], v[138:141], v[154:157], v[48:51]
	v_mfma_f32_16x16x32_bf16 v[44:47], v[130:133], v[162:165], v[44:47]
	v_mfma_f32_16x16x32_bf16 v[40:43], v[138:141], v[162:165], v[40:43]
	v_mfma_f32_16x16x32_bf16 v[36:39], v[130:133], v[170:173], v[36:39]
	v_mfma_f32_16x16x32_bf16 v[32:35], v[138:141], v[170:173], v[32:35]
	v_mfma_f32_16x16x32_bf16 v[60:63], v[134:137], v[150:153], v[60:63]
	v_mfma_f32_16x16x32_bf16 v[56:59], v[142:145], v[150:153], v[56:59]
	v_mfma_f32_16x16x32_bf16 v[52:55], v[134:137], v[158:161], v[52:55]
	v_mfma_f32_16x16x32_bf16 v[48:51], v[142:145], v[158:161], v[48:51]
	v_mfma_f32_16x16x32_bf16 v[44:47], v[134:137], v[166:169], v[44:47]
	v_mfma_f32_16x16x32_bf16 v[40:43], v[142:145], v[166:169], v[40:43]
	v_mfma_f32_16x16x32_bf16 v[36:39], v[134:137], v[174:177], v[36:39]
	v_mfma_f32_16x16x32_bf16 v[32:35], v[142:145], v[174:177], v[32:35]
	s_barrier
	s_mov_b64 s[76:77], 0x32e60180
	s_add_i32 s73, s3, 0x1c000
	s_mov_b32 m0, s73
	s_mov_b64 s[76:77], 0x32f10180
	s_add_u32 s94, s10, 0x32e60180
	s_addc_u32 s95, s11, 0
	global_load_lds_dwordx4 v194, s[94:95]
	s_mov_b32 m0, s60
	s_nop 0
	s_add_u32 s94, s10, 0x32f10180
	s_addc_u32 s95, s11, 0
	global_load_lds_dwordx4 v194, s[94:95]
	s_waitcnt vmcnt(6)
	s_barrier
	v_mfma_f32_16x16x32_bf16 v[28:31], v[178:181], v[146:149], v[28:31]
	v_mfma_f32_16x16x32_bf16 v[24:27], v[186:189], v[146:149], v[24:27]
	v_mfma_f32_16x16x32_bf16 v[20:23], v[178:181], v[154:157], v[20:23]
	v_mfma_f32_16x16x32_bf16 v[16:19], v[186:189], v[154:157], v[16:19]
	v_mfma_f32_16x16x32_bf16 v[12:15], v[178:181], v[162:165], v[12:15]
	v_mfma_f32_16x16x32_bf16 v[8:11], v[186:189], v[162:165], v[8:11]
	v_mfma_f32_16x16x32_bf16 v[4:7], v[178:181], v[170:173], v[4:7]
	v_mfma_f32_16x16x32_bf16 v[0:3], v[186:189], v[170:173], v[0:3]
	v_mfma_f32_16x16x32_bf16 v[28:31], v[182:185], v[150:153], v[28:31]
	v_mfma_f32_16x16x32_bf16 v[24:27], v[196:199], v[150:153], v[24:27]
	v_mfma_f32_16x16x32_bf16 v[20:23], v[182:185], v[158:161], v[20:23]
	v_mfma_f32_16x16x32_bf16 v[16:19], v[196:199], v[158:161], v[16:19]
	v_mfma_f32_16x16x32_bf16 v[12:15], v[182:185], v[166:169], v[12:15]
	v_mfma_f32_16x16x32_bf16 v[8:11], v[196:199], v[166:169], v[8:11]
	v_mfma_f32_16x16x32_bf16 v[4:7], v[182:185], v[174:177], v[4:7]
	v_mfma_f32_16x16x32_bf16 v[0:3], v[196:199], v[174:177], v[0:3]
	s_add_i32 s68, s68, 2
	s_add_u32 s10, s10, 0x100
	s_addc_u32 s11, s11, 0
	s_add_u32 s58, s58, 0x100
	s_addc_u32 s59, s59, 0
	s_cmpk_gt_u32 s68, 0x53
	s_barrier
	s_cbranch_scc0 .LBB0_123
	ds_read_b128 v[130:133], v201 offset:0
	ds_read_b128 v[134:137], v201 offset:0x400
	ds_read_b128 v[138:141], v201 offset:0x800
	ds_read_b128 v[142:145], v201 offset:0xc00
	ds_read_b128 v[146:149], v202 offset:0
	ds_read_b128 v[150:153], v202 offset:0x400
	ds_read_b128 v[154:157], v202 offset:0x800
	ds_read_b128 v[158:161], v202 offset:0xc00
	ds_read_b128 v[162:165], v202 offset:0x1000
	ds_read_b128 v[166:169], v202 offset:0x1400
	ds_read_b128 v[170:173], v202 offset:0x1800
	s_mov_b64 s[10:11], 0x162b80
	s_mov_b32 m0, s74
	ds_read_b128 v[174:177], v202 offset:0x1c00
	v_lshl_add_u64 v[178:179], v[128:129], 0, s[10:11]
	s_mov_b64 s[10:11], 0x212b80
	global_load_lds_dwordx4 v[178:179], off
	v_lshl_add_u64 v[128:129], v[128:129], 0, s[10:11]
	s_mov_b32 m0, s61
	s_mul_i32 s10, s63, 0x2c0000
	global_load_lds_dwordx4 v[128:129], off
	s_mul_hi_i32 s11, s63, 0x2c0000
	s_add_u32 s10, s46, s10
	s_barrier
	s_waitcnt lgkmcnt(0)
	s_addc_u32 s11, s47, s11
	s_mul_i32 s58, s64, 0x2c0000
	s_mul_hi_i32 s59, s64, 0x2c0000
	s_add_u32 s58, s12, s58
	s_addc_u32 s59, s13, s59
	v_mfma_f32_16x16x32_bf16 v[124:127], v[130:133], v[146:149], v[124:127]
	v_mfma_f32_16x16x32_bf16 v[120:123], v[138:141], v[146:149], v[120:123]
	v_mfma_f32_16x16x32_bf16 v[116:119], v[130:133], v[154:157], v[116:119]
	v_mfma_f32_16x16x32_bf16 v[112:115], v[138:141], v[154:157], v[112:115]
	v_mfma_f32_16x16x32_bf16 v[108:111], v[130:133], v[162:165], v[108:111]
	v_mfma_f32_16x16x32_bf16 v[104:107], v[138:141], v[162:165], v[104:107]
	v_mfma_f32_16x16x32_bf16 v[100:103], v[130:133], v[170:173], v[100:103]
	v_mfma_f32_16x16x32_bf16 v[96:99], v[138:141], v[170:173], v[96:99]
	v_mfma_f32_16x16x32_bf16 v[124:127], v[134:137], v[150:153], v[124:127]
	v_mfma_f32_16x16x32_bf16 v[120:123], v[142:145], v[150:153], v[120:123]
	v_mfma_f32_16x16x32_bf16 v[116:119], v[134:137], v[158:161], v[116:119]
	v_mfma_f32_16x16x32_bf16 v[112:115], v[142:145], v[158:161], v[112:115]
	v_mfma_f32_16x16x32_bf16 v[108:111], v[134:137], v[166:169], v[108:111]
	v_mfma_f32_16x16x32_bf16 v[104:107], v[142:145], v[166:169], v[104:107]
	v_mfma_f32_16x16x32_bf16 v[100:103], v[134:137], v[174:177], v[100:103]
	v_mfma_f32_16x16x32_bf16 v[96:99], v[142:145], v[174:177], v[96:99]
	s_barrier
	ds_read_b128 v[178:181], v203 offset:0
	ds_read_b128 v[182:185], v203 offset:0x400
	ds_read_b128 v[186:189], v203 offset:0x800
	ds_read_b128 v[196:199], v203 offset:0xc00
	s_barrier
; #define WAIT_V(n) asm volatile("s_waitcnt vmcnt(%0)" ::"n"(n) : "memory")
; #define SCHED() __builtin_amdgcn_sched_barrier(0)
; #define LGKM(n) asm volatile("s_waitcnt lgkmcnt(%0)" ::"n"(n) : "memory")
; #define LDA(b, h) do { const unsigned pa_ = lds0 + SLOTA(b, h) + wr * 8192 + laneoff; _Pragma("unroll") for (int m = 0; m < 4; ++m)   \
;       _Pragma("unroll") for (int k = 0; k < 2; ++k) DSR(At[m][k], pa_, m * 2048 + k * 1024); } while (0)
; #define LDB(dst, b, h) do { const unsigned pb_ = lds0 + SLOTB(b, h) + wc * 4096 + laneoff; _Pragma("unroll") for (int n = 0; n < 2; ++n) \
;       _Pragma("unroll") for (int k = 0; k < 2; ++k) DSR(dst[n][k], pb_, n * 2048 + k * 1024); } while (0)
; #define BAR __builtin_amdgcn_s_barrier()
; #define LGKM(n) asm volatile("s_waitcnt lgkmcnt(%0)" ::"n"(n) : "memory")
; template <int EPI, bool SWP> ...
;     ...
;     LDB(B1, 0, 1); BAR; LGKM(0); SCHED(); MMA(0, 1, B1); BAR; SCHED();
;     LDA(0, 1); WAIT_V(4); BAR; LGKM(0); SCHED(); MMA(1, 0, B0); MMA(1, 1, B1); BAR; SCHED(); }
;   { LDB(B0, 1, 0); LDA(1, 0); WAIT_V(2); BAR; LGKM(0); SCHED(); MMA(0, 0, B0); BAR; SCHED();
	s_waitcnt lgkmcnt(0)
	v_mfma_f32_16x16x32_bf16 v[92:95], v[178:181], v[146:149], v[92:95]
	v_mfma_f32_16x16x32_bf16 v[88:91], v[186:189], v[146:149], v[88:91]
	v_mfma_f32_16x16x32_bf16 v[84:87], v[178:181], v[154:157], v[84:87]
	v_mfma_f32_16x16x32_bf16 v[80:83], v[186:189], v[154:157], v[80:83]
	v_mfma_f32_16x16x32_bf16 v[76:79], v[178:181], v[162:165], v[76:79]
	v_mfma_f32_16x16x32_bf16 v[72:75], v[186:189], v[162:165], v[72:75]
	v_mfma_f32_16x16x32_bf16 v[68:71], v[178:181], v[170:173], v[68:71]
	v_mfma_f32_16x16x32_bf16 v[64:67], v[186:189], v[170:173], v[64:67]
	v_mfma_f32_16x16x32_bf16 v[92:95], v[182:185], v[150:153], v[92:95]
	v_mfma_f32_16x16x32_bf16 v[88:91], v[196:199], v[150:153], v[88:91]
	v_mfma_f32_16x16x32_bf16 v[84:87], v[182:185], v[158:161], v[84:87]
	v_mfma_f32_16x16x32_bf16 v[80:83], v[196:199], v[158:161], v[80:83]
	v_mfma_f32_16x16x32_bf16 v[76:79], v[182:185], v[166:169], v[76:79]
	v_mfma_f32_16x16x32_bf16 v[72:75], v[196:199], v[166:169], v[72:75]
	v_mfma_f32_16x16x32_bf16 v[68:71], v[182:185], v[174:177], v[68:71]
	v_mfma_f32_16x16x32_bf16 v[64:67], v[196:199], v[174:177], v[64:67]
	s_barrier
	ds_read_b128 v[146:149], v204 offset:0
	ds_read_b128 v[150:153], v204 offset:0x400
	ds_read_b128 v[154:157], v204 offset:0x800
	ds_read_b128 v[158:161], v204 offset:0xc00
	ds_read_b128 v[162:165], v204 offset:0x1000
	ds_read_b128 v[166:169], v204 offset:0x1400
	ds_read_b128 v[170:173], v204 offset:0x1800
	ds_read_b128 v[174:177], v204 offset:0x1c00
	s_waitcnt vmcnt(4)
	s_barrier
	s_waitcnt lgkmcnt(0)
	v_mfma_f32_16x16x32_bf16 v[60:63], v[130:133], v[146:149], v[60:63]
	v_mfma_f32_16x16x32_bf16 v[56:59], v[138:141], v[146:149], v[56:59]
	v_mfma_f32_16x16x32_bf16 v[52:55], v[130:133], v[154:157], v[52:55]
	v_mfma_f32_16x16x32_bf16 v[48:51], v[138:141], v[154:157], v[48:51]
	v_mfma_f32_16x16x32_bf16 v[44:47], v[130:133], v[162:165], v[44:47]
	v_mfma_f32_16x16x32_bf16 v[40:43], v[138:141], v[162:165], v[40:43]
	v_mfma_f32_16x16x32_bf16 v[36:39], v[130:133], v[170:173], v[36:39]
	v_mfma_f32_16x16x32_bf16 v[32:35], v[138:141], v[170:173], v[32:35]
	v_mfma_f32_16x16x32_bf16 v[60:63], v[134:137], v[150:153], v[60:63]
	v_mfma_f32_16x16x32_bf16 v[56:59], v[142:145], v[150:153], v[56:59]
	v_mfma_f32_16x16x32_bf16 v[52:55], v[134:137], v[158:161], v[52:55]
	v_mfma_f32_16x16x32_bf16 v[48:51], v[142:145], v[158:161], v[48:51]
	v_mfma_f32_16x16x32_bf16 v[44:47], v[134:137], v[166:169], v[44:47]
	v_mfma_f32_16x16x32_bf16 v[40:43], v[142:145], v[166:169], v[40:43]
	v_mfma_f32_16x16x32_bf16 v[36:39], v[134:137], v[174:177], v[36:39]
	v_mfma_f32_16x16x32_bf16 v[32:35], v[142:145], v[174:177], v[32:35]
	v_mfma_f32_16x16x32_bf16 v[28:31], v[178:181], v[146:149], v[28:31]
	v_mfma_f32_16x16x32_bf16 v[24:27], v[186:189], v[146:149], v[24:27]
	v_mfma_f32_16x16x32_bf16 v[20:23], v[178:181], v[154:157], v[20:23]
	v_mfma_f32_16x16x32_bf16 v[16:19], v[186:189], v[154:157], v[16:19]
	v_mfma_f32_16x16x32_bf16 v[12:15], v[178:181], v[162:165], v[12:15]
	v_mfma_f32_16x16x32_bf16 v[8:11], v[186:189], v[162:165], v[8:11]
	v_mfma_f32_16x16x32_bf16 v[4:7], v[178:181], v[170:173], v[4:7]
	v_mfma_f32_16x16x32_bf16 v[0:3], v[186:189], v[170:173], v[0:3]
	v_mfma_f32_16x16x32_bf16 v[28:31], v[182:185], v[150:153], v[28:31]
	v_mfma_f32_16x16x32_bf16 v[24:27], v[196:199], v[150:153], v[24:27]
	v_mfma_f32_16x16x32_bf16 v[20:23], v[182:185], v[158:161], v[20:23]
	v_mfma_f32_16x16x32_bf16 v[16:19], v[196:199], v[158:161], v[16:19]
	v_mfma_f32_16x16x32_bf16 v[12:15], v[182:185], v[166:169], v[12:15]
	v_mfma_f32_16x16x32_bf16 v[8:11], v[196:199], v[166:169], v[8:11]
	v_mfma_f32_16x16x32_bf16 v[4:7], v[182:185], v[174:177], v[4:7]
	v_mfma_f32_16x16x32_bf16 v[0:3], v[196:199], v[174:177], v[0:3]
	s_barrier
	ds_read_b128 v[128:131], v205 offset:0
	ds_read_b128 v[132:135], v205 offset:0x400
	ds_read_b128 v[136:139], v205 offset:0x800
	ds_read_b128 v[140:143], v205 offset:0xc00
	ds_read_b128 v[160:163], v206 offset:0
	ds_read_b128 v[164:167], v206 offset:0x400
	ds_read_b128 v[168:171], v206 offset:0x800
	ds_read_b128 v[172:175], v206 offset:0xc00
	ds_read_b128 v[176:179], v206 offset:0x1000
	ds_read_b128 v[180:183], v206 offset:0x1400
	ds_read_b128 v[184:187], v206 offset:0x1800
	ds_read_b128 v[188:191], v206 offset:0x1c00
	s_waitcnt vmcnt(2)
	s_barrier
; #define WAIT_V(n) asm volatile("s_waitcnt vmcnt(%0)" ::"n"(n) : "memory")
; #define SCHED() __builtin_amdgcn_sched_barrier(0)
; #define LGKM(n) asm volatile("s_waitcnt lgkmcnt(%0)" ::"n"(n) : "memory")
; #define STAGE_AX(AG, b, h, kt) do { _Pragma("unroll") for (int i = 0; i < 2; ++i)                                    \
;       __builtin_amdgcn_global_load_lds((const unsigned*)(((AG) + ((size_t)(kt) * (BK * 2) + (size_t)((h) * 2 + i) * 128 * lda)) + aoff), \
;                                        (unsigned*)(shm + SLOTA(b, h) + wid * 1024 + i * 8192), 16, 0, 0); } while (0)
; #define STAGE_BX(BG, b, h, kt) do { _Pragma("unroll") for (int i = 0; i < 2; ++i)                                    \
;       __builtin_amdgcn_global_load_lds((const unsigned*)(((BG) + ((size_t)(kt) * (BK * 2) + (size_t)((h) * 2 + i) * 128 * K)) + boff),   \
;                                        (unsigned*)(shm + SLOTB(b, h) + wid * 1024 + i * 8192), 16, 0, 0); } while (0)
; #define LDA(b, h) do { const unsigned pa_ = lds0 + SLOTA(b, h) + wr * 8192 + laneoff; _Pragma("unroll") for (int m = 0; m < 4; ++m)   \
;       _Pragma("unroll") for (int k = 0; k < 2; ++k) DSR(At[m][k], pa_, m * 2048 + k * 1024); } while (0)
; #define LDB(dst, b, h) do { const unsigned pb_ = lds0 + SLOTB(b, h) + wc * 4096 + laneoff; _Pragma("unroll") for (int n = 0; n < 2; ++n) \
;       _Pragma("unroll") for (int k = 0; k < 2; ++k) DSR(dst[n][k], pb_, n * 2048 + k * 1024); } while (0)
; #define BAR __builtin_amdgcn_s_barrier()
; #define LGKM(n) asm volatile("s_waitcnt lgkmcnt(%0)" ::"n"(n) : "memory")
; template <int EPI, bool SWP> ...
;     ...
;   { LDB(B0, 1, 0); LDA(1, 0); WAIT_V(2); BAR; LGKM(0); SCHED(); MMA(0, 0, B0); BAR; SCHED();
;     LDB(B1, 1, 1); WAIT_V(0); BAR; LGKM(0); SCHED(); MMA(0, 1, B1); BAR; SCHED();
;     LDA(1, 1);
;     if (has_next) { STAGE_BX(Bg_n, 0, 0, 0); STAGE_AX(Ag_n, 0, 0, 0); STAGE_BX(Bg_n, 0, 1, 0); STAGE_AX(Ag_n, 0, 1, 0); }
	s_waitcnt lgkmcnt(0)
	v_mfma_f32_16x16x32_bf16 v[124:127], v[128:131], v[160:163], v[124:127]
	v_mfma_f32_16x16x32_bf16 v[120:123], v[136:139], v[160:163], v[120:123]
	v_mfma_f32_16x16x32_bf16 v[116:119], v[128:131], v[168:171], v[116:119]
	v_mfma_f32_16x16x32_bf16 v[112:115], v[136:139], v[168:171], v[112:115]
	v_mfma_f32_16x16x32_bf16 v[108:111], v[128:131], v[176:179], v[108:111]
	v_mfma_f32_16x16x32_bf16 v[104:107], v[136:139], v[176:179], v[104:107]
	v_mfma_f32_16x16x32_bf16 v[100:103], v[128:131], v[184:187], v[100:103]
	v_mfma_f32_16x16x32_bf16 v[96:99], v[136:139], v[184:187], v[96:99]
	v_mfma_f32_16x16x32_bf16 v[124:127], v[132:135], v[164:167], v[124:127]
	v_mfma_f32_16x16x32_bf16 v[120:123], v[140:143], v[164:167], v[120:123]
	v_mfma_f32_16x16x32_bf16 v[116:119], v[132:135], v[172:175], v[116:119]
	v_mfma_f32_16x16x32_bf16 v[112:115], v[140:143], v[172:175], v[112:115]
	v_mfma_f32_16x16x32_bf16 v[108:111], v[132:135], v[180:183], v[108:111]
	v_mfma_f32_16x16x32_bf16 v[104:107], v[140:143], v[180:183], v[104:107]
	v_mfma_f32_16x16x32_bf16 v[100:103], v[132:135], v[188:191], v[100:103]
	v_mfma_f32_16x16x32_bf16 v[96:99], v[140:143], v[188:191], v[96:99]
	s_barrier
	ds_read_b128 v[144:147], v207 offset:0
	ds_read_b128 v[148:151], v207 offset:0x400
	ds_read_b128 v[152:155], v207 offset:0x800
	ds_read_b128 v[156:159], v207 offset:0xc00
	s_waitcnt vmcnt(0)
	s_barrier
	s_waitcnt lgkmcnt(0)
	v_mfma_f32_16x16x32_bf16 v[92:95], v[144:147], v[160:163], v[92:95]
	v_mfma_f32_16x16x32_bf16 v[88:91], v[152:155], v[160:163], v[88:91]
	v_mfma_f32_16x16x32_bf16 v[84:87], v[144:147], v[168:171], v[84:87]
	v_mfma_f32_16x16x32_bf16 v[80:83], v[152:155], v[168:171], v[80:83]
	v_mfma_f32_16x16x32_bf16 v[76:79], v[144:147], v[176:179], v[76:79]
	v_mfma_f32_16x16x32_bf16 v[72:75], v[152:155], v[176:179], v[72:75]
	v_mfma_f32_16x16x32_bf16 v[68:71], v[144:147], v[184:187], v[68:71]
	v_mfma_f32_16x16x32_bf16 v[64:67], v[152:155], v[184:187], v[64:67]
	v_mfma_f32_16x16x32_bf16 v[92:95], v[148:151], v[164:167], v[92:95]
	v_mfma_f32_16x16x32_bf16 v[88:91], v[156:159], v[164:167], v[88:91]
	v_mfma_f32_16x16x32_bf16 v[84:87], v[148:151], v[172:175], v[84:87]
	v_mfma_f32_16x16x32_bf16 v[80:83], v[156:159], v[172:175], v[80:83]
	v_mfma_f32_16x16x32_bf16 v[76:79], v[148:151], v[180:183], v[76:79]
	v_mfma_f32_16x16x32_bf16 v[72:75], v[156:159], v[180:183], v[72:75]
	v_mfma_f32_16x16x32_bf16 v[68:71], v[148:151], v[188:191], v[68:71]
	v_mfma_f32_16x16x32_bf16 v[64:67], v[156:159], v[188:191], v[64:67]
	s_barrier
	ds_read_b128 v[184:187], v208 offset:0
	ds_read_b128 v[188:191], v208 offset:0x400
	ds_read_b128 v[176:179], v208 offset:0x800
	ds_read_b128 v[180:183], v208 offset:0xc00
	ds_read_b128 v[168:171], v208 offset:0x1000
	ds_read_b128 v[172:175], v208 offset:0x1400
	ds_read_b128 v[160:163], v208 offset:0x1800
	ds_read_b128 v[164:167], v208 offset:0x1c00
	s_and_b64 vcc, exec, s[48:49]
	v_lshl_add_u64 v[196:197], s[58:59], 0, v[192:193]
	v_lshl_add_u64 v[198:199], s[10:11], 0, v[192:193]
	s_cbranch_vccz .LBB0_126
	s_mov_b32 m0, s17
	v_lshl_add_u64 v[220:221], v[196:197], 0, s[14:15]
	global_load_lds_dwordx4 v[196:197], off
	s_mov_b32 m0, s18
	s_nop 0
	global_load_lds_dwordx4 v[220:221], off
	s_mov_b32 m0, s3
	v_lshl_add_u64 v[220:221], v[198:199], 0, s[14:15]
	global_load_lds_dwordx4 v[198:199], off
	s_mov_b32 m0, s19
	s_nop 0
	global_load_lds_dwordx4 v[220:221], off
	v_lshl_add_u64 v[220:221], v[196:197], 0, s[20:21]
	s_mov_b32 m0, s69
	s_nop 0
	global_load_lds_dwordx4 v[220:221], off
	v_lshl_add_u64 v[220:221], v[196:197], 0, s[22:23]
	s_mov_b32 m0, s30
	s_nop 0
	global_load_lds_dwordx4 v[220:221], off
	v_lshl_add_u64 v[220:221], v[198:199], 0, s[20:21]
	s_mov_b32 m0, s71
	s_nop 0
	global_load_lds_dwordx4 v[220:221], off
	v_lshl_add_u64 v[220:221], v[198:199], 0, s[22:23]
	s_mov_b32 m0, s31
	s_nop 0
	global_load_lds_dwordx4 v[220:221], off

; #define WAIT_V(n) asm volatile("s_waitcnt vmcnt(%0)" ::"n"(n) : "memory")
; #define SCHED() __builtin_amdgcn_sched_barrier(0)
; #define LGKM(n) asm volatile("s_waitcnt lgkmcnt(%0)" ::"n"(n) : "memory")
; #define STAGE_A(b, h, kt) STAGE_AX(Ag, b, h, kt)
; #define STAGE_B(b, h, kt) STAGE_BX(Bg, b, h, kt)
; #define LDA(b, h) do { const unsigned pa_ = lds0 + SLOTA(b, h) + wr * 8192 + laneoff; _Pragma("unroll") for (int m = 0; m < 4; ++m)   \
;       _Pragma("unroll") for (int k = 0; k < 2; ++k) DSR(At[m][k], pa_, m * 2048 + k * 1024); } while (0)
; #define LDB(dst, b, h) do { const unsigned pb_ = lds0 + SLOTB(b, h) + wc * 4096 + laneoff; _Pragma("unroll") for (int n = 0; n < 2; ++n) \
;       _Pragma("unroll") for (int k = 0; k < 2; ++k) DSR(dst[n][k], pb_, n * 2048 + k * 1024); } while (0)
; #define BAR __builtin_amdgcn_s_barrier()
; #define LGKM(n) asm volatile("s_waitcnt lgkmcnt(%0)" ::"n"(n) : "memory")
; template <int EPI, bool SWP> ...
;     ...
;   for (int t = 0; t < nt - 2; t += 2) {
;     LDB(B0, 0, 0); LDA(0, 0); STAGE_A(1, 1, t + 1);
;     LGKM(8); BAR; LGKM(0); SCHED(); MMA(0, 0, B0); BAR; SCHED();
;     LDB(B1, 0, 1); STAGE_B(0, 0, t + 2);
;     BAR; LGKM(0); SCHED(); MMA(0, 1, B1); BAR; SCHED();
;     LDA(0, 1); STAGE_A(0, 0, t + 2);
;     BAR; LGKM(0); SCHED(); MMA(1, 0, B0); BAR; SCHED();
;     STAGE_B(0, 1, t + 2);
;     WAIT_V(6); BAR; SCHED(); MMA(1, 1, B1); BAR; SCHED();
.LBB0_197:
	ds_read_b128 v[128:131], v203 offset:0
	ds_read_b128 v[132:135], v203 offset:0x400
	ds_read_b128 v[136:139], v203 offset:0x800
	ds_read_b128 v[140:143], v203 offset:0xc00
	ds_read_b128 v[144:147], v204 offset:0
	ds_read_b128 v[148:151], v204 offset:0x400
	ds_read_b128 v[152:155], v204 offset:0x800
	ds_read_b128 v[156:159], v204 offset:0xc00
	ds_read_b128 v[160:163], v204 offset:0x1000
	ds_read_b128 v[164:167], v204 offset:0x1400
	ds_read_b128 v[168:171], v204 offset:0x1800
	v_lshl_add_u64 v[200:201], s[12:13], 0, v[196:197]
	s_add_i32 vcc_lo, s69, 0xc000
	ds_read_b128 v[172:175], v204 offset:0x1c00
	s_mov_b32 m0, vcc_lo
	s_nop 0
	s_add_u32 s52, s12, s80
	s_addc_u32 s53, s13, s81
	global_load_lds_dwordx4 v196, s[52:53]
	s_mov_b32 m0, s17
	s_nop 0
	s_add_u32 s52, s12, s82
	s_addc_u32 s53, s13, s83
	global_load_lds_dwordx4 v196, s[52:53]
	s_waitcnt lgkmcnt(8)
	s_barrier
	s_waitcnt lgkmcnt(0)
	v_mfma_f32_16x16x32_bf16 v[124:127], v[128:131], v[144:147], v[124:127]
	v_mfma_f32_16x16x32_bf16 v[120:123], v[136:139], v[144:147], v[120:123]
	v_mfma_f32_16x16x32_bf16 v[116:119], v[128:131], v[152:155], v[116:119]
	v_mfma_f32_16x16x32_bf16 v[112:115], v[136:139], v[152:155], v[112:115]
	v_mfma_f32_16x16x32_bf16 v[108:111], v[128:131], v[160:163], v[108:111]
	v_mfma_f32_16x16x32_bf16 v[104:107], v[136:139], v[160:163], v[104:107]
	v_mfma_f32_16x16x32_bf16 v[100:103], v[128:131], v[168:171], v[100:103]
	v_mfma_f32_16x16x32_bf16 v[96:99], v[136:139], v[168:171], v[96:99]
	v_mfma_f32_16x16x32_bf16 v[124:127], v[132:135], v[148:151], v[124:127]
	v_mfma_f32_16x16x32_bf16 v[120:123], v[140:143], v[148:151], v[120:123]
	v_mfma_f32_16x16x32_bf16 v[116:119], v[132:135], v[156:159], v[116:119]
	v_mfma_f32_16x16x32_bf16 v[112:115], v[140:143], v[156:159], v[112:115]
	v_mfma_f32_16x16x32_bf16 v[108:111], v[132:135], v[164:167], v[108:111]
	v_mfma_f32_16x16x32_bf16 v[104:107], v[140:143], v[164:167], v[104:107]
	v_mfma_f32_16x16x32_bf16 v[100:103], v[132:135], v[172:175], v[100:103]
	v_mfma_f32_16x16x32_bf16 v[96:99], v[140:143], v[172:175], v[96:99]
	s_barrier
	ds_read_b128 v[176:179], v205 offset:0
	ds_read_b128 v[180:183], v205 offset:0x400
	ds_read_b128 v[184:187], v205 offset:0x800
	v_lshl_add_u64 v[224:225], s[6:7], 0, v[196:197]
	s_mov_b32 m0, s68
	ds_read_b128 v[188:191], v205 offset:0xc00
	s_add_u32 s52, s6, s84
	s_addc_u32 s53, s7, s85
	global_load_lds_dwordx4 v196, s[52:53]
	s_mov_b32 m0, s64
	s_nop 0
	s_add_u32 s52, s6, s86
	s_addc_u32 s53, s7, s87
	global_load_lds_dwordx4 v196, s[52:53]
	s_barrier
	s_waitcnt lgkmcnt(0)
	v_mfma_f32_16x16x32_bf16 v[92:95], v[176:179], v[144:147], v[92:95]
	v_mfma_f32_16x16x32_bf16 v[88:91], v[184:187], v[144:147], v[88:91]
	v_mfma_f32_16x16x32_bf16 v[84:87], v[176:179], v[152:155], v[84:87]
	v_mfma_f32_16x16x32_bf16 v[80:83], v[184:187], v[152:155], v[80:83]
	v_mfma_f32_16x16x32_bf16 v[76:79], v[176:179], v[160:163], v[76:79]
	v_mfma_f32_16x16x32_bf16 v[72:75], v[184:187], v[160:163], v[72:75]
	v_mfma_f32_16x16x32_bf16 v[68:71], v[176:179], v[168:171], v[68:71]
	v_mfma_f32_16x16x32_bf16 v[64:67], v[184:187], v[168:171], v[64:67]
	v_mfma_f32_16x16x32_bf16 v[92:95], v[180:183], v[148:151], v[92:95]
	v_mfma_f32_16x16x32_bf16 v[88:91], v[188:191], v[148:151], v[88:91]
	v_mfma_f32_16x16x32_bf16 v[84:87], v[180:183], v[156:159], v[84:87]
	v_mfma_f32_16x16x32_bf16 v[80:83], v[188:191], v[156:159], v[80:83]
	v_mfma_f32_16x16x32_bf16 v[76:79], v[180:183], v[164:167], v[76:79]
	v_mfma_f32_16x16x32_bf16 v[72:75], v[188:191], v[164:167], v[72:75]
	v_mfma_f32_16x16x32_bf16 v[68:71], v[180:183], v[172:175], v[68:71]
	v_mfma_f32_16x16x32_bf16 v[64:67], v[188:191], v[172:175], v[64:67]
	s_barrier
	ds_read_b128 v[144:147], v206 offset:0
	ds_read_b128 v[148:151], v206 offset:0x400
	ds_read_b128 v[152:155], v206 offset:0x800
	ds_read_b128 v[156:159], v206 offset:0xc00
	ds_read_b128 v[160:163], v206 offset:0x1000
	ds_read_b128 v[164:167], v206 offset:0x1400
	ds_read_b128 v[168:171], v206 offset:0x1800
	s_mov_b32 m0, s69
	ds_read_b128 v[172:175], v206 offset:0x1c00
	s_add_u32 s52, s12, s88
	s_addc_u32 s53, s13, s89
	global_load_lds_dwordx4 v196, s[52:53]
	s_mov_b32 m0, s65
	s_nop 0
	s_add_u32 s52, s12, s90
	s_addc_u32 s53, s13, s91
	global_load_lds_dwordx4 v196, s[52:53]
	s_barrier
	s_waitcnt lgkmcnt(0)
	v_mfma_f32_16x16x32_bf16 v[60:63], v[128:131], v[144:147], v[60:63]
	v_mfma_f32_16x16x32_bf16 v[56:59], v[136:139], v[144:147], v[56:59]
	v_mfma_f32_16x16x32_bf16 v[52:55], v[128:131], v[152:155], v[52:55]
	v_mfma_f32_16x16x32_bf16 v[48:51], v[136:139], v[152:155], v[48:51]
	v_mfma_f32_16x16x32_bf16 v[44:47], v[128:131], v[160:163], v[44:47]
	v_mfma_f32_16x16x32_bf16 v[40:43], v[136:139], v[160:163], v[40:43]
	v_mfma_f32_16x16x32_bf16 v[36:39], v[128:131], v[168:171], v[36:39]
	v_mfma_f32_16x16x32_bf16 v[32:35], v[136:139], v[168:171], v[32:35]
	v_mfma_f32_16x16x32_bf16 v[60:63], v[132:135], v[148:151], v[60:63]
	v_mfma_f32_16x16x32_bf16 v[56:59], v[140:143], v[148:151], v[56:59]
	v_mfma_f32_16x16x32_bf16 v[52:55], v[132:135], v[156:159], v[52:55]
	v_mfma_f32_16x16x32_bf16 v[48:51], v[140:143], v[156:159], v[48:51]
	v_mfma_f32_16x16x32_bf16 v[44:47], v[132:135], v[164:167], v[44:47]
	v_mfma_f32_16x16x32_bf16 v[40:43], v[140:143], v[164:167], v[40:43]
	v_mfma_f32_16x16x32_bf16 v[36:39], v[132:135], v[172:175], v[36:39]
	v_mfma_f32_16x16x32_bf16 v[32:35], v[140:143], v[172:175], v[32:35]
	s_barrier
	s_add_i32 s23, s69, 0x14000
	s_mov_b32 m0, s23
	s_nop 0
	s_add_u32 s52, s6, s92
	s_addc_u32 s53, s7, s93
	global_load_lds_dwordx4 v196, s[52:53]
	s_mov_b32 m0, s50
	s_nop 0
	s_add_u32 s52, s6, s94
	s_addc_u32 s53, s7, s95
	global_load_lds_dwordx4 v196, s[52:53]
	s_waitcnt vmcnt(6)
	s_barrier
; #define WAIT_V(n) asm volatile("s_waitcnt vmcnt(%0)" ::"n"(n) : "memory")
; #define SCHED() __builtin_amdgcn_sched_barrier(0)
; #define LGKM(n) asm volatile("s_waitcnt lgkmcnt(%0)" ::"n"(n) : "memory")
; #define STAGE_A(b, h, kt) STAGE_AX(Ag, b, h, kt)
; #define STAGE_B(b, h, kt) STAGE_BX(Bg, b, h, kt)
; #define LDA(b, h) do { const unsigned pa_ = lds0 + SLOTA(b, h) + wr * 8192 + laneoff; _Pragma("unroll") for (int m = 0; m < 4; ++m)   \
;       _Pragma("unroll") for (int k = 0; k < 2; ++k) DSR(At[m][k], pa_, m * 2048 + k * 1024); } while (0)
; #define LDB(dst, b, h) do { const unsigned pb_ = lds0 + SLOTB(b, h) + wc * 4096 + laneoff; _Pragma("unroll") for (int n = 0; n < 2; ++n) \
;       _Pragma("unroll") for (int k = 0; k < 2; ++k) DSR(dst[n][k], pb_, n * 2048 + k * 1024); } while (0)
; #define BAR __builtin_amdgcn_s_barrier()
; #define LGKM(n) asm volatile("s_waitcnt lgkmcnt(%0)" ::"n"(n) : "memory")
; template <int EPI, bool SWP> ...
;     ...
;     WAIT_V(6); BAR; SCHED(); MMA(1, 1, B1); BAR; SCHED();
;     LDB(B0, 1, 0); LDA(1, 0); STAGE_A(0, 1, t + 2);
;     LGKM(8); BAR; LGKM(0); SCHED(); MMA(0, 0, B0); BAR; SCHED();
;     LDB(B1, 1, 1); STAGE_B(1, 0, t + 3);
;     BAR; LGKM(0); SCHED(); MMA(0, 1, B1); BAR; SCHED();
;     LDA(1, 1); STAGE_A(1, 0, t + 3);
;     BAR; LGKM(0); SCHED(); MMA(1, 0, B0); BAR; SCHED();
	v_mfma_f32_16x16x32_bf16 v[28:31], v[176:179], v[144:147], v[28:31]
	v_mfma_f32_16x16x32_bf16 v[24:27], v[184:187], v[144:147], v[24:27]
	v_mfma_f32_16x16x32_bf16 v[20:23], v[176:179], v[152:155], v[20:23]
	v_mfma_f32_16x16x32_bf16 v[16:19], v[184:187], v[152:155], v[16:19]
	v_mfma_f32_16x16x32_bf16 v[12:15], v[176:179], v[160:163], v[12:15]
	v_mfma_f32_16x16x32_bf16 v[8:11], v[184:187], v[160:163], v[8:11]
	v_mfma_f32_16x16x32_bf16 v[4:7], v[176:179], v[168:171], v[4:7]
	v_mfma_f32_16x16x32_bf16 v[0:3], v[184:187], v[168:171], v[0:3]
	v_mfma_f32_16x16x32_bf16 v[28:31], v[180:183], v[148:151], v[28:31]
	v_mfma_f32_16x16x32_bf16 v[24:27], v[188:191], v[148:151], v[24:27]
	v_mfma_f32_16x16x32_bf16 v[20:23], v[180:183], v[156:159], v[20:23]
	v_mfma_f32_16x16x32_bf16 v[16:19], v[188:191], v[156:159], v[16:19]
	v_mfma_f32_16x16x32_bf16 v[12:15], v[180:183], v[164:167], v[12:15]
	v_mfma_f32_16x16x32_bf16 v[8:11], v[188:191], v[164:167], v[8:11]
	v_mfma_f32_16x16x32_bf16 v[4:7], v[180:183], v[172:175], v[4:7]
	v_mfma_f32_16x16x32_bf16 v[0:3], v[188:191], v[172:175], v[0:3]
	s_barrier
	ds_read_b128 v[128:131], v207 offset:0
	ds_read_b128 v[132:135], v207 offset:0x400
	ds_read_b128 v[136:139], v207 offset:0x800
	ds_read_b128 v[140:143], v207 offset:0xc00
	ds_read_b128 v[144:147], v208 offset:0
	ds_read_b128 v[148:151], v208 offset:0x400
	ds_read_b128 v[152:155], v208 offset:0x800
	ds_read_b128 v[156:159], v208 offset:0xc00
	ds_read_b128 v[160:163], v208 offset:0x1000
	ds_read_b128 v[164:167], v208 offset:0x1400
	ds_read_b128 v[168:171], v208 offset:0x1800
	s_add_i32 s29, s69, 0x4000
	ds_read_b128 v[172:175], v208 offset:0x1c00
	s_mov_b32 m0, s29
	s_nop 0
	s_add_u32 s52, s12, s96
	s_addc_u32 s53, s13, s97
	global_load_lds_dwordx4 v196, s[52:53]
	s_mov_b32 m0, s51
	s_nop 0
	s_add_u32 s52, s12, s44
	s_addc_u32 s53, s13, s45
	global_load_lds_dwordx4 v196, s[52:53]
	s_waitcnt lgkmcnt(8)
	s_barrier
	s_waitcnt lgkmcnt(0)
	v_mfma_f32_16x16x32_bf16 v[124:127], v[128:131], v[144:147], v[124:127]
	v_mfma_f32_16x16x32_bf16 v[120:123], v[136:139], v[144:147], v[120:123]
	v_mfma_f32_16x16x32_bf16 v[116:119], v[128:131], v[152:155], v[116:119]
	v_mfma_f32_16x16x32_bf16 v[112:115], v[136:139], v[152:155], v[112:115]
	v_mfma_f32_16x16x32_bf16 v[108:111], v[128:131], v[160:163], v[108:111]
	v_mfma_f32_16x16x32_bf16 v[104:107], v[136:139], v[160:163], v[104:107]
	v_mfma_f32_16x16x32_bf16 v[100:103], v[128:131], v[168:171], v[100:103]
	v_mfma_f32_16x16x32_bf16 v[96:99], v[136:139], v[168:171], v[96:99]
	v_mfma_f32_16x16x32_bf16 v[124:127], v[132:135], v[148:151], v[124:127]
	v_mfma_f32_16x16x32_bf16 v[120:123], v[140:143], v[148:151], v[120:123]
	v_mfma_f32_16x16x32_bf16 v[116:119], v[132:135], v[156:159], v[116:119]
	v_mfma_f32_16x16x32_bf16 v[112:115], v[140:143], v[156:159], v[112:115]
	v_mfma_f32_16x16x32_bf16 v[108:111], v[132:135], v[164:167], v[108:111]
	v_mfma_f32_16x16x32_bf16 v[104:107], v[140:143], v[164:167], v[104:107]
	v_mfma_f32_16x16x32_bf16 v[100:103], v[132:135], v[172:175], v[100:103]
	v_mfma_f32_16x16x32_bf16 v[96:99], v[140:143], v[172:175], v[96:99]
	s_barrier
	ds_read_b128 v[176:179], v209 offset:0
	ds_read_b128 v[180:183], v209 offset:0x400
	ds_read_b128 v[184:187], v209 offset:0x800
	s_add_i32 s25, s69, 0x18000
	ds_read_b128 v[188:191], v209 offset:0xc00
	s_mov_b32 m0, s25
	s_nop 0
	s_add_u32 s52, s6, s58
	s_addc_u32 s53, s7, s59
	global_load_lds_dwordx4 v196, s[52:53]
	s_mov_b32 m0, s66
	s_nop 0
	s_add_u32 s52, s6, s60
	s_addc_u32 s53, s7, s61
	global_load_lds_dwordx4 v196, s[52:53]
	s_barrier
	s_waitcnt lgkmcnt(0)
	v_mfma_f32_16x16x32_bf16 v[92:95], v[176:179], v[144:147], v[92:95]
	v_mfma_f32_16x16x32_bf16 v[88:91], v[184:187], v[144:147], v[88:91]
	v_mfma_f32_16x16x32_bf16 v[84:87], v[176:179], v[152:155], v[84:87]
	v_mfma_f32_16x16x32_bf16 v[80:83], v[184:187], v[152:155], v[80:83]
	v_mfma_f32_16x16x32_bf16 v[76:79], v[176:179], v[160:163], v[76:79]
	v_mfma_f32_16x16x32_bf16 v[72:75], v[184:187], v[160:163], v[72:75]
	v_mfma_f32_16x16x32_bf16 v[68:71], v[176:179], v[168:171], v[68:71]
	v_mfma_f32_16x16x32_bf16 v[64:67], v[184:187], v[168:171], v[64:67]
	v_mfma_f32_16x16x32_bf16 v[92:95], v[180:183], v[148:151], v[92:95]
	v_mfma_f32_16x16x32_bf16 v[88:91], v[188:191], v[148:151], v[88:91]
	v_mfma_f32_16x16x32_bf16 v[84:87], v[180:183], v[156:159], v[84:87]
	v_mfma_f32_16x16x32_bf16 v[80:83], v[188:191], v[156:159], v[80:83]
	v_mfma_f32_16x16x32_bf16 v[76:79], v[180:183], v[164:167], v[76:79]
	v_mfma_f32_16x16x32_bf16 v[72:75], v[188:191], v[164:167], v[72:75]
	v_mfma_f32_16x16x32_bf16 v[68:71], v[180:183], v[172:175], v[68:71]
	v_mfma_f32_16x16x32_bf16 v[64:67], v[188:191], v[172:175], v[64:67]
	s_barrier
	ds_read_b128 v[144:147], v210 offset:0
	ds_read_b128 v[148:151], v210 offset:0x400
	ds_read_b128 v[152:155], v210 offset:0x800
	ds_read_b128 v[156:159], v210 offset:0xc00
	ds_read_b128 v[160:163], v210 offset:0x1000
	ds_read_b128 v[164:167], v210 offset:0x1400
	ds_read_b128 v[168:171], v210 offset:0x1800
	s_add_i32 s48, s69, 0x8000
	ds_read_b128 v[172:175], v210 offset:0x1c00
	s_mov_b32 m0, s48
	v_lshl_add_u64 v[200:201], v[200:201], 0, s[4:5]
	s_add_u32 s52, s12, s0
	s_addc_u32 s53, s13, s1
	global_load_lds_dwordx4 v196, s[52:53]
	s_mov_b32 m0, s67
	s_nop 0
	s_add_u32 s52, s12, s4
	s_addc_u32 s53, s13, s5
	global_load_lds_dwordx4 v196, s[52:53]
	s_barrier
; #define WAIT_V(n) asm volatile("s_waitcnt vmcnt(%0)" ::"n"(n) : "memory")
; #define SCHED() __builtin_amdgcn_sched_barrier(0)
; #define LGKM(n) asm volatile("s_waitcnt lgkmcnt(%0)" ::"n"(n) : "memory")
; #define STAGE_A(b, h, kt) STAGE_AX(Ag, b, h, kt)
; #define STAGE_B(b, h, kt) STAGE_BX(Bg, b, h, kt)
; #define LDA(b, h) do { const unsigned pa_ = lds0 + SLOTA(b, h) + wr * 8192 + laneoff; _Pragma("unroll") for (int m = 0; m < 4; ++m)   \
;       _Pragma("unroll") for (int k = 0; k < 2; ++k) DSR(At[m][k], pa_, m * 2048 + k * 1024); } while (0)
; #define LDB(dst, b, h) do { const unsigned pb_ = lds0 + SLOTB(b, h) + wc * 4096 + laneoff; _Pragma("unroll") for (int n = 0; n < 2; ++n) \
;       _Pragma("unroll") for (int k = 0; k < 2; ++k) DSR(dst[n][k], pb_, n * 2048 + k * 1024); } while (0)
; #define BAR __builtin_amdgcn_s_barrier()
; #define LGKM(n) asm volatile("s_waitcnt lgkmcnt(%0)" ::"n"(n) : "memory")
; template <int EPI, bool SWP> ...
;     ...
;     STAGE_B(1, 1, t + 3);
;     WAIT_V(6); BAR; SCHED(); MMA(1, 1, B1); BAR; SCHED();
;   }
;   { LDB(B0, 0, 0); LDA(0, 0); STAGE_A(1, 1, nt - 1);
;     BAR; LGKM(0); SCHED(); MMA(0, 0, B0); BAR; SCHED();
;     LDB(B1, 0, 1); BAR; LGKM(0); SCHED(); MMA(0, 1, B1); BAR; SCHED();
;     LDA(0, 1); WAIT_V(4); BAR; LGKM(0); SCHED(); MMA(1, 0, B0); MMA(1, 1, B1); BAR; SCHED(); }
	s_waitcnt lgkmcnt(0)
	v_mfma_f32_16x16x32_bf16 v[60:63], v[128:131], v[144:147], v[60:63]
	v_mfma_f32_16x16x32_bf16 v[56:59], v[136:139], v[144:147], v[56:59]
	v_mfma_f32_16x16x32_bf16 v[52:55], v[128:131], v[152:155], v[52:55]
	v_mfma_f32_16x16x32_bf16 v[48:51], v[136:139], v[152:155], v[48:51]
	v_mfma_f32_16x16x32_bf16 v[44:47], v[128:131], v[160:163], v[44:47]
	v_mfma_f32_16x16x32_bf16 v[40:43], v[136:139], v[160:163], v[40:43]
	v_mfma_f32_16x16x32_bf16 v[36:39], v[128:131], v[168:171], v[36:39]
	v_mfma_f32_16x16x32_bf16 v[32:35], v[136:139], v[168:171], v[32:35]
	v_mfma_f32_16x16x32_bf16 v[60:63], v[132:135], v[148:151], v[60:63]
	v_mfma_f32_16x16x32_bf16 v[56:59], v[140:143], v[148:151], v[56:59]
	v_mfma_f32_16x16x32_bf16 v[52:55], v[132:135], v[156:159], v[52:55]
	v_mfma_f32_16x16x32_bf16 v[48:51], v[140:143], v[156:159], v[48:51]
	v_mfma_f32_16x16x32_bf16 v[44:47], v[132:135], v[164:167], v[44:47]
	v_mfma_f32_16x16x32_bf16 v[40:43], v[140:143], v[164:167], v[40:43]
	v_mfma_f32_16x16x32_bf16 v[36:39], v[132:135], v[172:175], v[36:39]
	v_mfma_f32_16x16x32_bf16 v[32:35], v[140:143], v[172:175], v[32:35]
	s_barrier
	s_add_i32 s49, s69, 0x1c000
	s_mov_b32 m0, s49
	s_nop 0
	s_add_u32 s52, s6, s34
	s_addc_u32 s53, s7, s35
	global_load_lds_dwordx4 v196, s[52:53]
	s_mov_b32 m0, s16
	s_nop 0
	s_add_u32 s52, s6, s14
	s_addc_u32 s53, s7, s15
	global_load_lds_dwordx4 v196, s[52:53]
	s_waitcnt vmcnt(6)
	s_barrier
	v_mfma_f32_16x16x32_bf16 v[28:31], v[176:179], v[144:147], v[28:31]
	v_mfma_f32_16x16x32_bf16 v[24:27], v[184:187], v[144:147], v[24:27]
	v_mfma_f32_16x16x32_bf16 v[20:23], v[176:179], v[152:155], v[20:23]
	v_mfma_f32_16x16x32_bf16 v[16:19], v[184:187], v[152:155], v[16:19]
	v_mfma_f32_16x16x32_bf16 v[12:15], v[176:179], v[160:163], v[12:15]
	v_mfma_f32_16x16x32_bf16 v[8:11], v[184:187], v[160:163], v[8:11]
	v_mfma_f32_16x16x32_bf16 v[4:7], v[176:179], v[168:171], v[4:7]
	v_mfma_f32_16x16x32_bf16 v[0:3], v[184:187], v[168:171], v[0:3]
	v_mfma_f32_16x16x32_bf16 v[28:31], v[180:183], v[148:151], v[28:31]
	v_mfma_f32_16x16x32_bf16 v[24:27], v[188:191], v[148:151], v[24:27]
	v_mfma_f32_16x16x32_bf16 v[20:23], v[180:183], v[156:159], v[20:23]
	v_mfma_f32_16x16x32_bf16 v[16:19], v[188:191], v[156:159], v[16:19]
	v_mfma_f32_16x16x32_bf16 v[12:15], v[180:183], v[164:167], v[12:15]
	v_mfma_f32_16x16x32_bf16 v[8:11], v[188:191], v[164:167], v[8:11]
	v_mfma_f32_16x16x32_bf16 v[4:7], v[180:183], v[172:175], v[4:7]
	v_mfma_f32_16x16x32_bf16 v[0:3], v[188:191], v[172:175], v[0:3]
	s_add_i32 s9, s9, 2
	s_add_u32 s6, s6, 0x100
	s_addc_u32 s7, s7, 0
	s_add_u32 s12, s12, 0x100
	s_addc_u32 s13, s13, 0
	s_cmp_gt_u32 s9, 27
	s_barrier
	s_cbranch_scc0 .LBB0_197
	ds_read_b128 v[128:131], v203 offset:0
	ds_read_b128 v[132:135], v203 offset:0x400
	ds_read_b128 v[136:139], v203 offset:0x800
	ds_read_b128 v[140:143], v203 offset:0xc00
	ds_read_b128 v[144:147], v204 offset:0
	ds_read_b128 v[148:151], v204 offset:0x400
	ds_read_b128 v[152:155], v204 offset:0x800
	ds_read_b128 v[156:159], v204 offset:0xc00
	ds_read_b128 v[160:163], v204 offset:0x1000
	ds_read_b128 v[164:167], v204 offset:0x1400
	v_lshl_add_u64 v[176:177], s[76:77], 0, v[192:193]
	ds_read_b128 v[168:171], v204 offset:0x1800
	s_mov_b64 s[6:7], 0x80f80
	s_mov_b32 m0, vcc_lo
	ds_read_b128 v[172:175], v204 offset:0x1c00
	v_lshl_add_u64 v[178:179], v[176:177], 0, s[6:7]
	s_mov_b64 s[6:7], 0xc0f80
	global_load_lds_dwordx4 v[178:179], off
	v_lshl_add_u64 v[176:177], v[176:177], 0, s[6:7]
	s_mov_b32 m0, s17
	s_nop 0
	global_load_lds_dwordx4 v[176:177], off
	s_barrier
	s_waitcnt lgkmcnt(0)
	v_mfma_f32_16x16x32_bf16 v[124:127], v[128:131], v[144:147], v[124:127]
	v_mfma_f32_16x16x32_bf16 v[120:123], v[136:139], v[144:147], v[120:123]
	v_mfma_f32_16x16x32_bf16 v[116:119], v[128:131], v[152:155], v[116:119]
	v_mfma_f32_16x16x32_bf16 v[112:115], v[136:139], v[152:155], v[112:115]
	v_mfma_f32_16x16x32_bf16 v[108:111], v[128:131], v[160:163], v[108:111]
	v_mfma_f32_16x16x32_bf16 v[104:107], v[136:139], v[160:163], v[104:107]
	v_mfma_f32_16x16x32_bf16 v[100:103], v[128:131], v[168:171], v[100:103]
	v_mfma_f32_16x16x32_bf16 v[96:99], v[136:139], v[168:171], v[96:99]
	v_mfma_f32_16x16x32_bf16 v[124:127], v[132:135], v[148:151], v[124:127]
	v_mfma_f32_16x16x32_bf16 v[120:123], v[140:143], v[148:151], v[120:123]
	v_mfma_f32_16x16x32_bf16 v[116:119], v[132:135], v[156:159], v[116:119]
	v_mfma_f32_16x16x32_bf16 v[112:115], v[140:143], v[156:159], v[112:115]
	v_mfma_f32_16x16x32_bf16 v[108:111], v[132:135], v[164:167], v[108:111]
	v_mfma_f32_16x16x32_bf16 v[104:107], v[140:143], v[164:167], v[104:107]
	v_mfma_f32_16x16x32_bf16 v[100:103], v[132:135], v[172:175], v[100:103]
	v_mfma_f32_16x16x32_bf16 v[96:99], v[140:143], v[172:175], v[96:99]
	s_barrier
	ds_read_b128 v[176:179], v205 offset:0
	ds_read_b128 v[180:183], v205 offset:0x400
	ds_read_b128 v[184:187], v205 offset:0x800
	ds_read_b128 v[188:191], v205 offset:0xc00
	s_barrier
	s_waitcnt lgkmcnt(0)
	v_mfma_f32_16x16x32_bf16 v[92:95], v[176:179], v[144:147], v[92:95]
	v_mfma_f32_16x16x32_bf16 v[88:91], v[184:187], v[144:147], v[88:91]
	v_mfma_f32_16x16x32_bf16 v[84:87], v[176:179], v[152:155], v[84:87]
	v_mfma_f32_16x16x32_bf16 v[80:83], v[184:187], v[152:155], v[80:83]
	v_mfma_f32_16x16x32_bf16 v[76:79], v[176:179], v[160:163], v[76:79]
	v_mfma_f32_16x16x32_bf16 v[72:75], v[184:187], v[160:163], v[72:75]
	v_mfma_f32_16x16x32_bf16 v[68:71], v[176:179], v[168:171], v[68:71]
	v_mfma_f32_16x16x32_bf16 v[64:67], v[184:187], v[168:171], v[64:67]
	v_mfma_f32_16x16x32_bf16 v[92:95], v[180:183], v[148:151], v[92:95]
	v_mfma_f32_16x16x32_bf16 v[88:91], v[188:191], v[148:151], v[88:91]
	v_mfma_f32_16x16x32_bf16 v[84:87], v[180:183], v[156:159], v[84:87]
	v_mfma_f32_16x16x32_bf16 v[80:83], v[188:191], v[156:159], v[80:83]
	v_mfma_f32_16x16x32_bf16 v[76:79], v[180:183], v[164:167], v[76:79]
	v_mfma_f32_16x16x32_bf16 v[72:75], v[188:191], v[164:167], v[72:75]
	v_mfma_f32_16x16x32_bf16 v[68:71], v[180:183], v[172:175], v[68:71]
	v_mfma_f32_16x16x32_bf16 v[64:67], v[188:191], v[172:175], v[64:67]
	s_barrier
; #define WAIT_V(n) asm volatile("s_waitcnt vmcnt(%0)" ::"n"(n) : "memory")
; #define SCHED() __builtin_amdgcn_sched_barrier(0)
; #define LGKM(n) asm volatile("s_waitcnt lgkmcnt(%0)" ::"n"(n) : "memory")
; #define LDA(b, h) do { const unsigned pa_ = lds0 + SLOTA(b, h) + wr * 8192 + laneoff; _Pragma("unroll") for (int m = 0; m < 4; ++m)   \
;       _Pragma("unroll") for (int k = 0; k < 2; ++k) DSR(At[m][k], pa_, m * 2048 + k * 1024); } while (0)
; #define LDB(dst, b, h) do { const unsigned pb_ = lds0 + SLOTB(b, h) + wc * 4096 + laneoff; _Pragma("unroll") for (int n = 0; n < 2; ++n) \
;       _Pragma("unroll") for (int k = 0; k < 2; ++k) DSR(dst[n][k], pb_, n * 2048 + k * 1024); } while (0)
; #define BAR __builtin_amdgcn_s_barrier()
; #define LGKM(n) asm volatile("s_waitcnt lgkmcnt(%0)" ::"n"(n) : "memory")
; template <int EPI, bool SWP> ...
;     ...
;     LDA(0, 1); WAIT_V(4); BAR; LGKM(0); SCHED(); MMA(1, 0, B0); MMA(1, 1, B1); BAR; SCHED(); }
;   { LDB(B0, 1, 0); LDA(1, 0); WAIT_V(2); BAR; LGKM(0); SCHED(); MMA(0, 0, B0); BAR; SCHED();
	ds_read_b128 v[144:147], v206 offset:0
	ds_read_b128 v[148:151], v206 offset:0x400
	ds_read_b128 v[152:155], v206 offset:0x800
	ds_read_b128 v[156:159], v206 offset:0xc00
	ds_read_b128 v[160:163], v206 offset:0x1000
	ds_read_b128 v[164:167], v206 offset:0x1400
	ds_read_b128 v[168:171], v206 offset:0x1800
	ds_read_b128 v[172:175], v206 offset:0x1c00
	s_waitcnt vmcnt(4)
	s_barrier
	s_waitcnt lgkmcnt(0)
	v_mfma_f32_16x16x32_bf16 v[60:63], v[128:131], v[144:147], v[60:63]
	v_mfma_f32_16x16x32_bf16 v[56:59], v[136:139], v[144:147], v[56:59]
	v_mfma_f32_16x16x32_bf16 v[52:55], v[128:131], v[152:155], v[52:55]
	v_mfma_f32_16x16x32_bf16 v[48:51], v[136:139], v[152:155], v[48:51]
	v_mfma_f32_16x16x32_bf16 v[44:47], v[128:131], v[160:163], v[44:47]
	v_mfma_f32_16x16x32_bf16 v[40:43], v[136:139], v[160:163], v[40:43]
	v_mfma_f32_16x16x32_bf16 v[36:39], v[128:131], v[168:171], v[36:39]
	v_mfma_f32_16x16x32_bf16 v[32:35], v[136:139], v[168:171], v[32:35]
	v_mfma_f32_16x16x32_bf16 v[60:63], v[132:135], v[148:151], v[60:63]
	v_mfma_f32_16x16x32_bf16 v[56:59], v[140:143], v[148:151], v[56:59]
	v_mfma_f32_16x16x32_bf16 v[52:55], v[132:135], v[156:159], v[52:55]
	v_mfma_f32_16x16x32_bf16 v[48:51], v[140:143], v[156:159], v[48:51]
	v_mfma_f32_16x16x32_bf16 v[44:47], v[132:135], v[164:167], v[44:47]
	v_mfma_f32_16x16x32_bf16 v[40:43], v[140:143], v[164:167], v[40:43]
	v_mfma_f32_16x16x32_bf16 v[36:39], v[132:135], v[172:175], v[36:39]
	v_mfma_f32_16x16x32_bf16 v[32:35], v[140:143], v[172:175], v[32:35]
	v_mfma_f32_16x16x32_bf16 v[28:31], v[176:179], v[144:147], v[28:31]
	v_mfma_f32_16x16x32_bf16 v[24:27], v[184:187], v[144:147], v[24:27]
	v_mfma_f32_16x16x32_bf16 v[20:23], v[176:179], v[152:155], v[20:23]
	v_mfma_f32_16x16x32_bf16 v[16:19], v[184:187], v[152:155], v[16:19]
	v_mfma_f32_16x16x32_bf16 v[12:15], v[176:179], v[160:163], v[12:15]
	v_mfma_f32_16x16x32_bf16 v[8:11], v[184:187], v[160:163], v[8:11]
	v_mfma_f32_16x16x32_bf16 v[4:7], v[176:179], v[168:171], v[4:7]
	v_mfma_f32_16x16x32_bf16 v[0:3], v[184:187], v[168:171], v[0:3]
	v_mfma_f32_16x16x32_bf16 v[28:31], v[180:183], v[148:151], v[28:31]
	v_mfma_f32_16x16x32_bf16 v[24:27], v[188:191], v[148:151], v[24:27]
	v_mfma_f32_16x16x32_bf16 v[20:23], v[180:183], v[156:159], v[20:23]
	v_mfma_f32_16x16x32_bf16 v[16:19], v[188:191], v[156:159], v[16:19]
	v_mfma_f32_16x16x32_bf16 v[12:15], v[180:183], v[164:167], v[12:15]
	v_mfma_f32_16x16x32_bf16 v[8:11], v[188:191], v[164:167], v[8:11]
	v_mfma_f32_16x16x32_bf16 v[4:7], v[180:183], v[172:175], v[4:7]
	v_mfma_f32_16x16x32_bf16 v[0:3], v[188:191], v[172:175], v[0:3]
	s_barrier
	ds_read_b128 v[128:131], v207 offset:0
	ds_read_b128 v[132:135], v207 offset:0x400
	ds_read_b128 v[136:139], v207 offset:0x800
	ds_read_b128 v[140:143], v207 offset:0xc00
	ds_read_b128 v[160:163], v208 offset:0
	ds_read_b128 v[164:167], v208 offset:0x400
	ds_read_b128 v[168:171], v208 offset:0x800
	ds_read_b128 v[172:175], v208 offset:0xc00
	ds_read_b128 v[176:179], v208 offset:0x1000
	ds_read_b128 v[180:183], v208 offset:0x1400
	ds_read_b128 v[184:187], v208 offset:0x1800
	ds_read_b128 v[188:191], v208 offset:0x1c00
	s_waitcnt vmcnt(2)
	s_barrier
; #define WAIT_V(n) asm volatile("s_waitcnt vmcnt(%0)" ::"n"(n) : "memory")
; #define SCHED() __builtin_amdgcn_sched_barrier(0)
; #define LGKM(n) asm volatile("s_waitcnt lgkmcnt(%0)" ::"n"(n) : "memory")
; #define STAGE_AX(AG, b, h, kt) do { _Pragma("unroll") for (int i = 0; i < 2; ++i)                                    \
;       __builtin_amdgcn_global_load_lds((const unsigned*)(((AG) + ((size_t)(kt) * (BK * 2) + (size_t)((h) * 2 + i) * 128 * lda)) + aoff), \
;                                        (unsigned*)(shm + SLOTA(b, h) + wid * 1024 + i * 8192), 16, 0, 0); } while (0)
; #define STAGE_BX(BG, b, h, kt) do { _Pragma("unroll") for (int i = 0; i < 2; ++i)                                    \
;       __builtin_amdgcn_global_load_lds((const unsigned*)(((BG) + ((size_t)(kt) * (BK * 2) + (size_t)((h) * 2 + i) * 128 * K)) + boff),   \
;                                        (unsigned*)(shm + SLOTB(b, h) + wid * 1024 + i * 8192), 16, 0, 0); } while (0)
; #define LDA(b, h) do { const unsigned pa_ = lds0 + SLOTA(b, h) + wr * 8192 + laneoff; _Pragma("unroll") for (int m = 0; m < 4; ++m)   \
;       _Pragma("unroll") for (int k = 0; k < 2; ++k) DSR(At[m][k], pa_, m * 2048 + k * 1024); } while (0)
; #define LDB(dst, b, h) do { const unsigned pb_ = lds0 + SLOTB(b, h) + wc * 4096 + laneoff; _Pragma("unroll") for (int n = 0; n < 2; ++n) \
;       _Pragma("unroll") for (int k = 0; k < 2; ++k) DSR(dst[n][k], pb_, n * 2048 + k * 1024); } while (0)
; #define BAR __builtin_amdgcn_s_barrier()
; #define LGKM(n) asm volatile("s_waitcnt lgkmcnt(%0)" ::"n"(n) : "memory")
; template <int EPI, bool SWP> ...
;     ...
;   { LDB(B0, 1, 0); LDA(1, 0); WAIT_V(2); BAR; LGKM(0); SCHED(); MMA(0, 0, B0); BAR; SCHED();
;     LDB(B1, 1, 1); WAIT_V(0); BAR; LGKM(0); SCHED(); MMA(0, 1, B1); BAR; SCHED();
;     LDA(1, 1);
;     if (has_next) { STAGE_BX(Bg_n, 0, 0, 0); STAGE_AX(Ag_n, 0, 0, 0); STAGE_BX(Bg_n, 0, 1, 0); STAGE_AX(Ag_n, 0, 1, 0); }
;     BAR; LGKM(0); SCHED(); MMA(1, 0, B0); MMA(1, 1, B1); BAR; SCHED(); }
;   if (wr == 0) BAR;
;   if (has_next) {
;     STAGE_BX(Bg_n, 1, 0, 1); STAGE_AX(Ag_n, 1, 0, 1); STAGE_BX(Bg_n, 1, 1, 1);
;     if (e.nss > 0 && tid < 256) s_rstd_n[tid] = rsqrtf(ss_next * (1.f / DM) + 1e-6f);
	s_waitcnt lgkmcnt(0)
	v_mfma_f32_16x16x32_bf16 v[124:127], v[128:131], v[160:163], v[124:127]
	v_mfma_f32_16x16x32_bf16 v[120:123], v[136:139], v[160:163], v[120:123]
	v_mfma_f32_16x16x32_bf16 v[116:119], v[128:131], v[168:171], v[116:119]
	v_mfma_f32_16x16x32_bf16 v[112:115], v[136:139], v[168:171], v[112:115]
	v_mfma_f32_16x16x32_bf16 v[108:111], v[128:131], v[176:179], v[108:111]
	v_mfma_f32_16x16x32_bf16 v[104:107], v[136:139], v[176:179], v[104:107]
	v_mfma_f32_16x16x32_bf16 v[100:103], v[128:131], v[184:187], v[100:103]
	v_mfma_f32_16x16x32_bf16 v[96:99], v[136:139], v[184:187], v[96:99]
	v_mfma_f32_16x16x32_bf16 v[124:127], v[132:135], v[164:167], v[124:127]
	v_mfma_f32_16x16x32_bf16 v[120:123], v[140:143], v[164:167], v[120:123]
	v_mfma_f32_16x16x32_bf16 v[116:119], v[132:135], v[172:175], v[116:119]
	v_mfma_f32_16x16x32_bf16 v[112:115], v[140:143], v[172:175], v[112:115]
	v_mfma_f32_16x16x32_bf16 v[108:111], v[132:135], v[180:183], v[108:111]
	v_mfma_f32_16x16x32_bf16 v[104:107], v[140:143], v[180:183], v[104:107]
	v_mfma_f32_16x16x32_bf16 v[100:103], v[132:135], v[188:191], v[100:103]
	v_mfma_f32_16x16x32_bf16 v[96:99], v[140:143], v[188:191], v[96:99]
	s_barrier
	ds_read_b128 v[144:147], v209 offset:0
	ds_read_b128 v[148:151], v209 offset:0x400
	ds_read_b128 v[152:155], v209 offset:0x800
	ds_read_b128 v[156:159], v209 offset:0xc00
	s_waitcnt vmcnt(0)
	s_barrier
	s_waitcnt lgkmcnt(0)
	v_mfma_f32_16x16x32_bf16 v[92:95], v[144:147], v[160:163], v[92:95]
	v_mfma_f32_16x16x32_bf16 v[88:91], v[152:155], v[160:163], v[88:91]
	v_mfma_f32_16x16x32_bf16 v[84:87], v[144:147], v[168:171], v[84:87]
	v_mfma_f32_16x16x32_bf16 v[80:83], v[152:155], v[168:171], v[80:83]
	v_mfma_f32_16x16x32_bf16 v[76:79], v[144:147], v[176:179], v[76:79]
	v_mfma_f32_16x16x32_bf16 v[72:75], v[152:155], v[176:179], v[72:75]
	v_mfma_f32_16x16x32_bf16 v[68:71], v[144:147], v[184:187], v[68:71]
	v_mfma_f32_16x16x32_bf16 v[64:67], v[152:155], v[184:187], v[64:67]
	v_mfma_f32_16x16x32_bf16 v[92:95], v[148:151], v[164:167], v[92:95]
	v_mfma_f32_16x16x32_bf16 v[88:91], v[156:159], v[164:167], v[88:91]
	v_mfma_f32_16x16x32_bf16 v[84:87], v[148:151], v[172:175], v[84:87]
	v_mfma_f32_16x16x32_bf16 v[80:83], v[156:159], v[172:175], v[80:83]
	v_mfma_f32_16x16x32_bf16 v[76:79], v[148:151], v[180:183], v[76:79]
	v_mfma_f32_16x16x32_bf16 v[72:75], v[156:159], v[180:183], v[72:75]
	v_mfma_f32_16x16x32_bf16 v[68:71], v[148:151], v[188:191], v[68:71]
	v_mfma_f32_16x16x32_bf16 v[64:67], v[156:159], v[188:191], v[64:67]
	s_barrier
	ds_read_b128 v[184:187], v210 offset:0
	ds_read_b128 v[188:191], v210 offset:0x400
	ds_read_b128 v[176:179], v210 offset:0x800
	ds_read_b128 v[180:183], v210 offset:0xc00
	ds_read_b128 v[168:171], v210 offset:0x1000
	ds_read_b128 v[172:175], v210 offset:0x1400
	ds_read_b128 v[160:163], v210 offset:0x1800
	ds_read_b128 v[164:167], v210 offset:0x1c00
	s_and_b64 vcc, exec, s[70:71]
	s_cbranch_vccz .LBB0_200
	s_mov_b32 m0, s68
	v_lshl_add_u64 v[200:201], s[74:75], 0, v[192:193]
	s_mov_b64 s[6:7], 0x40000
	global_load_lds_dwordx4 v[200:201], off
	v_lshl_add_u64 v[224:225], v[200:201], 0, s[6:7]
	s_mov_b32 m0, s64
	s_mov_b64 s[12:13], 0xc0000
	global_load_lds_dwordx4 v[224:225], off
	v_lshl_add_u64 v[224:225], s[72:73], 0, v[192:193]
	s_mov_b32 m0, s69
	v_lshl_add_u64 v[226:227], v[224:225], 0, s[6:7]
	global_load_lds_dwordx4 v[224:225], off
	s_mov_b32 m0, s65
	s_mov_b64 s[6:7], 0x80000
	global_load_lds_dwordx4 v[226:227], off
	v_lshl_add_u64 v[226:227], v[200:201], 0, s[6:7]
	s_mov_b32 m0, s23
	v_lshl_add_u64 v[200:201], v[200:201], 0, s[12:13]
	global_load_lds_dwordx4 v[226:227], off
	s_mov_b32 m0, s50
	s_nop 0
	global_load_lds_dwordx4 v[200:201], off
	v_lshl_add_u64 v[200:201], v[224:225], 0, s[6:7]
	s_mov_b32 m0, s29
	s_nop 0
	global_load_lds_dwordx4 v[200:201], off
	v_lshl_add_u64 v[200:201], v[224:225], 0, s[12:13]
	s_mov_b32 m0, s51
	s_nop 0
	global_load_lds_dwordx4 v[200:201], off

; #define WAIT_V(n) asm volatile("s_waitcnt vmcnt(%0)" ::"n"(n) : "memory")
; #define SCHED() __builtin_amdgcn_sched_barrier(0)
; #define LGKM(n) asm volatile("s_waitcnt lgkmcnt(%0)" ::"n"(n) : "memory")
; #define STAGE_A(b, h, kt) STAGE_AX(Ag, b, h, kt)
; #define STAGE_B(b, h, kt) STAGE_BX(Bg, b, h, kt)
; #define LDA(b, h) do { const unsigned pa_ = lds0 + SLOTA(b, h) + wr * 8192 + laneoff; _Pragma("unroll") for (int m = 0; m < 4; ++m)   \
;       _Pragma("unroll") for (int k = 0; k < 2; ++k) DSR(At[m][k], pa_, m * 2048 + k * 1024); } while (0)
; #define LDB(dst, b, h) do { const unsigned pb_ = lds0 + SLOTB(b, h) + wc * 4096 + laneoff; _Pragma("unroll") for (int n = 0; n < 2; ++n) \
;       _Pragma("unroll") for (int k = 0; k < 2; ++k) DSR(dst[n][k], pb_, n * 2048 + k * 1024); } while (0)
; #define BAR __builtin_amdgcn_s_barrier()
; #define LGKM(n) asm volatile("s_waitcnt lgkmcnt(%0)" ::"n"(n) : "memory")
; template <int EPI, bool SWP> ...
;     ...
;   for (int t = 0; t < nt - 2; t += 2) {
;     LDB(B0, 0, 0); LDA(0, 0); STAGE_A(1, 1, t + 1);
;     LGKM(8); BAR; LGKM(0); SCHED(); MMA(0, 0, B0); BAR; SCHED();
;     LDB(B1, 0, 1); STAGE_B(0, 0, t + 2);
;     BAR; LGKM(0); SCHED(); MMA(0, 1, B1); BAR; SCHED();
;     LDA(0, 1); STAGE_A(0, 0, t + 2);
;     BAR; LGKM(0); SCHED(); MMA(1, 0, B0); BAR; SCHED();
;     STAGE_B(0, 1, t + 2);
;     WAIT_V(6); BAR; SCHED(); MMA(1, 1, B1); BAR; SCHED();
.LBB0_354:
	ds_read_b128 v[130:133], v222 offset:0
	ds_read_b128 v[134:137], v222 offset:0x400
	ds_read_b128 v[138:141], v222 offset:0x800
	ds_read_b128 v[142:145], v222 offset:0xc00
	ds_read_b128 v[146:149], v223 offset:0
	ds_read_b128 v[150:153], v223 offset:0x400
	ds_read_b128 v[154:157], v223 offset:0x800
	ds_read_b128 v[158:161], v223 offset:0xc00
	ds_read_b128 v[162:165], v223 offset:0x1000
	ds_read_b128 v[166:169], v223 offset:0x1400
	ds_read_b128 v[170:173], v223 offset:0x1800
	v_lshl_add_u64 v[194:195], s[48:49], 0, v[214:215]
	s_mov_b32 m0, s69
	ds_read_b128 v[174:177], v223 offset:0x1c00
	s_add_u32 s90, s48, s22
	s_addc_u32 s91, s49, s23
	global_load_lds_dwordx4 v214, s[90:91]
	s_mov_b32 m0, s70
	s_nop 0
	s_add_u32 s90, s48, s24
	s_addc_u32 s91, s49, s25
	global_load_lds_dwordx4 v214, s[90:91]
	s_waitcnt lgkmcnt(8)
	s_barrier
	s_waitcnt lgkmcnt(0)
	v_mfma_f32_16x16x32_bf16 v[124:127], v[130:133], v[146:149], v[124:127]
	v_mfma_f32_16x16x32_bf16 v[120:123], v[138:141], v[146:149], v[120:123]
	v_mfma_f32_16x16x32_bf16 v[116:119], v[130:133], v[154:157], v[116:119]
	v_mfma_f32_16x16x32_bf16 v[112:115], v[138:141], v[154:157], v[112:115]
	v_mfma_f32_16x16x32_bf16 v[108:111], v[130:133], v[162:165], v[108:111]
	v_mfma_f32_16x16x32_bf16 v[104:107], v[138:141], v[162:165], v[104:107]
	v_mfma_f32_16x16x32_bf16 v[100:103], v[130:133], v[170:173], v[100:103]
	v_mfma_f32_16x16x32_bf16 v[96:99], v[138:141], v[170:173], v[96:99]
	v_mfma_f32_16x16x32_bf16 v[124:127], v[134:137], v[150:153], v[124:127]
	v_mfma_f32_16x16x32_bf16 v[120:123], v[142:145], v[150:153], v[120:123]
	v_mfma_f32_16x16x32_bf16 v[116:119], v[134:137], v[158:161], v[116:119]
	v_mfma_f32_16x16x32_bf16 v[112:115], v[142:145], v[158:161], v[112:115]
	v_mfma_f32_16x16x32_bf16 v[108:111], v[134:137], v[166:169], v[108:111]
	v_mfma_f32_16x16x32_bf16 v[104:107], v[142:145], v[166:169], v[104:107]
	v_mfma_f32_16x16x32_bf16 v[100:103], v[134:137], v[174:177], v[100:103]
	v_mfma_f32_16x16x32_bf16 v[96:99], v[142:145], v[174:177], v[96:99]
	s_barrier
	ds_read_b128 v[178:181], v224 offset:0
	ds_read_b128 v[182:185], v224 offset:0x400
	ds_read_b128 v[186:189], v224 offset:0x800
	v_lshl_add_u64 v[196:197], s[50:51], 0, v[214:215]
	s_mov_b64 s[58:59], 0xe000100
	s_mov_b32 m0, s16
	ds_read_b128 v[190:193], v224 offset:0xc00
	s_mov_b64 s[58:59], 0xe020100
	s_add_u32 s90, s50, 0xe000100
	s_addc_u32 s91, s51, 0
	global_load_lds_dwordx4 v214, s[90:91]
	s_mov_b32 m0, s17
	s_nop 0
	s_add_u32 s90, s50, 0xe020100
	s_addc_u32 s91, s51, 0
	global_load_lds_dwordx4 v214, s[90:91]
	s_barrier
	s_waitcnt lgkmcnt(0)
	v_mfma_f32_16x16x32_bf16 v[92:95], v[178:181], v[146:149], v[92:95]
	v_mfma_f32_16x16x32_bf16 v[88:91], v[186:189], v[146:149], v[88:91]
	v_mfma_f32_16x16x32_bf16 v[84:87], v[178:181], v[154:157], v[84:87]
	v_mfma_f32_16x16x32_bf16 v[80:83], v[186:189], v[154:157], v[80:83]
	v_mfma_f32_16x16x32_bf16 v[76:79], v[178:181], v[162:165], v[76:79]
	v_mfma_f32_16x16x32_bf16 v[72:75], v[186:189], v[162:165], v[72:75]
	v_mfma_f32_16x16x32_bf16 v[68:71], v[178:181], v[170:173], v[68:71]
	v_mfma_f32_16x16x32_bf16 v[64:67], v[186:189], v[170:173], v[64:67]
	v_mfma_f32_16x16x32_bf16 v[92:95], v[182:185], v[150:153], v[92:95]
	v_mfma_f32_16x16x32_bf16 v[88:91], v[190:193], v[150:153], v[88:91]
	v_mfma_f32_16x16x32_bf16 v[84:87], v[182:185], v[158:161], v[84:87]
	v_mfma_f32_16x16x32_bf16 v[80:83], v[190:193], v[158:161], v[80:83]
	v_mfma_f32_16x16x32_bf16 v[76:79], v[182:185], v[166:169], v[76:79]
	v_mfma_f32_16x16x32_bf16 v[72:75], v[190:193], v[166:169], v[72:75]
	v_mfma_f32_16x16x32_bf16 v[68:71], v[182:185], v[174:177], v[68:71]
	v_mfma_f32_16x16x32_bf16 v[64:67], v[190:193], v[174:177], v[64:67]
	s_barrier
	ds_read_b128 v[146:149], v225 offset:0
	ds_read_b128 v[150:153], v225 offset:0x400
	ds_read_b128 v[154:157], v225 offset:0x800
	ds_read_b128 v[158:161], v225 offset:0xc00
	ds_read_b128 v[162:165], v225 offset:0x1000
	ds_read_b128 v[166:169], v225 offset:0x1400
	ds_read_b128 v[170:173], v225 offset:0x1800
	s_mov_b64 s[58:59], 0x100
	s_mov_b32 m0, s3
	ds_read_b128 v[174:177], v225 offset:0x1c00
	s_mov_b64 s[58:59], 0x20100
	s_add_u32 s90, s48, 0x100
	s_addc_u32 s91, s49, 0
	global_load_lds_dwordx4 v214, s[90:91]
	s_mov_b32 m0, s18
	s_nop 0
	s_add_u32 s90, s48, 0x20100
	s_addc_u32 s91, s49, 0
	global_load_lds_dwordx4 v214, s[90:91]
	s_barrier
	s_waitcnt lgkmcnt(0)
	v_mfma_f32_16x16x32_bf16 v[60:63], v[130:133], v[146:149], v[60:63]
	v_mfma_f32_16x16x32_bf16 v[56:59], v[138:141], v[146:149], v[56:59]
	v_mfma_f32_16x16x32_bf16 v[52:55], v[130:133], v[154:157], v[52:55]
	v_mfma_f32_16x16x32_bf16 v[48:51], v[138:141], v[154:157], v[48:51]
	v_mfma_f32_16x16x32_bf16 v[44:47], v[130:133], v[162:165], v[44:47]
	v_mfma_f32_16x16x32_bf16 v[40:43], v[138:141], v[162:165], v[40:43]
	v_mfma_f32_16x16x32_bf16 v[36:39], v[130:133], v[170:173], v[36:39]
	v_mfma_f32_16x16x32_bf16 v[32:35], v[138:141], v[170:173], v[32:35]
	v_mfma_f32_16x16x32_bf16 v[60:63], v[134:137], v[150:153], v[60:63]
	v_mfma_f32_16x16x32_bf16 v[56:59], v[142:145], v[150:153], v[56:59]
	v_mfma_f32_16x16x32_bf16 v[52:55], v[134:137], v[158:161], v[52:55]
	v_mfma_f32_16x16x32_bf16 v[48:51], v[142:145], v[158:161], v[48:51]
	v_mfma_f32_16x16x32_bf16 v[44:47], v[134:137], v[166:169], v[44:47]
	v_mfma_f32_16x16x32_bf16 v[40:43], v[142:145], v[166:169], v[40:43]
	v_mfma_f32_16x16x32_bf16 v[36:39], v[134:137], v[174:177], v[36:39]
	v_mfma_f32_16x16x32_bf16 v[32:35], v[142:145], v[174:177], v[32:35]
	s_barrier
; #define WAIT_V(n) asm volatile("s_waitcnt vmcnt(%0)" ::"n"(n) : "memory")
; #define SCHED() __builtin_amdgcn_sched_barrier(0)
; #define LGKM(n) asm volatile("s_waitcnt lgkmcnt(%0)" ::"n"(n) : "memory")
; #define STAGE_A(b, h, kt) STAGE_AX(Ag, b, h, kt)
; #define STAGE_B(b, h, kt) STAGE_BX(Bg, b, h, kt)
; #define LDA(b, h) do { const unsigned pa_ = lds0 + SLOTA(b, h) + wr * 8192 + laneoff; _Pragma("unroll") for (int m = 0; m < 4; ++m)   \
;       _Pragma("unroll") for (int k = 0; k < 2; ++k) DSR(At[m][k], pa_, m * 2048 + k * 1024); } while (0)
; #define LDB(dst, b, h) do { const unsigned pb_ = lds0 + SLOTB(b, h) + wc * 4096 + laneoff; _Pragma("unroll") for (int n = 0; n < 2; ++n) \
;       _Pragma("unroll") for (int k = 0; k < 2; ++k) DSR(dst[n][k], pb_, n * 2048 + k * 1024); } while (0)
; #define BAR __builtin_amdgcn_s_barrier()
; #define LGKM(n) asm volatile("s_waitcnt lgkmcnt(%0)" ::"n"(n) : "memory")
; template <int EPI, bool SWP> ...
;     ...
;     WAIT_V(6); BAR; SCHED(); MMA(1, 1, B1); BAR; SCHED();
;     LDB(B0, 1, 0); LDA(1, 0); STAGE_A(0, 1, t + 2);
;     LGKM(8); BAR; LGKM(0); SCHED(); MMA(0, 0, B0); BAR; SCHED();
;     LDB(B1, 1, 1); STAGE_B(1, 0, t + 3);
;     BAR; LGKM(0); SCHED(); MMA(0, 1, B1); BAR; SCHED();
;     LDA(1, 1); STAGE_A(1, 0, t + 3);
;     BAR; LGKM(0); SCHED(); MMA(1, 0, B0); BAR; SCHED();
	s_mov_b64 s[58:59], 0xe040100
	s_mov_b32 m0, s19
	s_mov_b64 s[58:59], 0xe060100
	s_add_u32 s90, s50, 0xe040100
	s_addc_u32 s91, s51, 0
	global_load_lds_dwordx4 v214, s[90:91]
	s_mov_b32 m0, s60
	s_nop 0
	s_add_u32 s90, s50, 0xe060100
	s_addc_u32 s91, s51, 0
	global_load_lds_dwordx4 v214, s[90:91]
	s_waitcnt vmcnt(6)
	s_barrier
	v_mfma_f32_16x16x32_bf16 v[28:31], v[178:181], v[146:149], v[28:31]
	v_mfma_f32_16x16x32_bf16 v[24:27], v[186:189], v[146:149], v[24:27]
	v_mfma_f32_16x16x32_bf16 v[20:23], v[178:181], v[154:157], v[20:23]
	v_mfma_f32_16x16x32_bf16 v[16:19], v[186:189], v[154:157], v[16:19]
	v_mfma_f32_16x16x32_bf16 v[12:15], v[178:181], v[162:165], v[12:15]
	v_mfma_f32_16x16x32_bf16 v[8:11], v[186:189], v[162:165], v[8:11]
	v_mfma_f32_16x16x32_bf16 v[4:7], v[178:181], v[170:173], v[4:7]
	v_mfma_f32_16x16x32_bf16 v[0:3], v[186:189], v[170:173], v[0:3]
	v_mfma_f32_16x16x32_bf16 v[28:31], v[182:185], v[150:153], v[28:31]
	v_mfma_f32_16x16x32_bf16 v[24:27], v[190:193], v[150:153], v[24:27]
	v_mfma_f32_16x16x32_bf16 v[20:23], v[182:185], v[158:161], v[20:23]
	v_mfma_f32_16x16x32_bf16 v[16:19], v[190:193], v[158:161], v[16:19]
	v_mfma_f32_16x16x32_bf16 v[12:15], v[182:185], v[166:169], v[12:15]
	v_mfma_f32_16x16x32_bf16 v[8:11], v[190:193], v[166:169], v[8:11]
	v_mfma_f32_16x16x32_bf16 v[4:7], v[182:185], v[174:177], v[4:7]
	v_mfma_f32_16x16x32_bf16 v[0:3], v[190:193], v[174:177], v[0:3]
	s_barrier
	ds_read_b128 v[130:133], v226 offset:0
	ds_read_b128 v[134:137], v226 offset:0x400
	ds_read_b128 v[138:141], v226 offset:0x800
	ds_read_b128 v[142:145], v226 offset:0xc00
	ds_read_b128 v[146:149], v227 offset:0
	ds_read_b128 v[150:153], v227 offset:0x400
	ds_read_b128 v[154:157], v227 offset:0x800
	ds_read_b128 v[158:161], v227 offset:0xc00
	ds_read_b128 v[162:165], v227 offset:0x1000
	ds_read_b128 v[166:169], v227 offset:0x1400
	ds_read_b128 v[170:173], v227 offset:0x1800
	s_mov_b64 s[58:59], 0x40100
	s_mov_b32 m0, s61
	ds_read_b128 v[174:177], v227 offset:0x1c00
	s_mov_b64 s[58:59], 0x60100
	s_add_u32 s90, s48, 0x40100
	s_addc_u32 s91, s49, 0
	global_load_lds_dwordx4 v214, s[90:91]
	s_mov_b32 m0, s62
	s_nop 0
	s_add_u32 s90, s48, 0x60100
	s_addc_u32 s91, s49, 0
	global_load_lds_dwordx4 v214, s[90:91]
	s_waitcnt lgkmcnt(8)
	s_barrier
	s_waitcnt lgkmcnt(0)
	v_mfma_f32_16x16x32_bf16 v[124:127], v[130:133], v[146:149], v[124:127]
	v_mfma_f32_16x16x32_bf16 v[120:123], v[138:141], v[146:149], v[120:123]
	v_mfma_f32_16x16x32_bf16 v[116:119], v[130:133], v[154:157], v[116:119]
	v_mfma_f32_16x16x32_bf16 v[112:115], v[138:141], v[154:157], v[112:115]
	v_mfma_f32_16x16x32_bf16 v[108:111], v[130:133], v[162:165], v[108:111]
	v_mfma_f32_16x16x32_bf16 v[104:107], v[138:141], v[162:165], v[104:107]
	v_mfma_f32_16x16x32_bf16 v[100:103], v[130:133], v[170:173], v[100:103]
	v_mfma_f32_16x16x32_bf16 v[96:99], v[138:141], v[170:173], v[96:99]
	v_mfma_f32_16x16x32_bf16 v[124:127], v[134:137], v[150:153], v[124:127]
	v_mfma_f32_16x16x32_bf16 v[120:123], v[142:145], v[150:153], v[120:123]
	v_mfma_f32_16x16x32_bf16 v[116:119], v[134:137], v[158:161], v[116:119]
	v_mfma_f32_16x16x32_bf16 v[112:115], v[142:145], v[158:161], v[112:115]
	v_mfma_f32_16x16x32_bf16 v[108:111], v[134:137], v[166:169], v[108:111]
	v_mfma_f32_16x16x32_bf16 v[104:107], v[142:145], v[166:169], v[104:107]
	v_mfma_f32_16x16x32_bf16 v[100:103], v[134:137], v[174:177], v[100:103]
	v_mfma_f32_16x16x32_bf16 v[96:99], v[142:145], v[174:177], v[96:99]
	s_barrier
	ds_read_b128 v[178:181], v229 offset:0
	ds_read_b128 v[182:185], v229 offset:0x400
	ds_read_b128 v[186:189], v229 offset:0x800
	s_mov_b64 s[58:59], 0xe000180
	s_mov_b32 m0, s63
	ds_read_b128 v[190:193], v229 offset:0xc00
	s_mov_b64 s[58:59], 0xe020180
	s_add_u32 s90, s50, 0xe000180
	s_addc_u32 s91, s51, 0
	global_load_lds_dwordx4 v214, s[90:91]
	s_mov_b32 m0, s64
	s_nop 0
	s_add_u32 s90, s50, 0xe020180
	s_addc_u32 s91, s51, 0
	global_load_lds_dwordx4 v214, s[90:91]
	s_barrier
	s_waitcnt lgkmcnt(0)
	v_mfma_f32_16x16x32_bf16 v[92:95], v[178:181], v[146:149], v[92:95]
	v_mfma_f32_16x16x32_bf16 v[88:91], v[186:189], v[146:149], v[88:91]
	v_mfma_f32_16x16x32_bf16 v[84:87], v[178:181], v[154:157], v[84:87]
	v_mfma_f32_16x16x32_bf16 v[80:83], v[186:189], v[154:157], v[80:83]
	v_mfma_f32_16x16x32_bf16 v[76:79], v[178:181], v[162:165], v[76:79]
	v_mfma_f32_16x16x32_bf16 v[72:75], v[186:189], v[162:165], v[72:75]
	v_mfma_f32_16x16x32_bf16 v[68:71], v[178:181], v[170:173], v[68:71]
	v_mfma_f32_16x16x32_bf16 v[64:67], v[186:189], v[170:173], v[64:67]
	v_mfma_f32_16x16x32_bf16 v[92:95], v[182:185], v[150:153], v[92:95]
	v_mfma_f32_16x16x32_bf16 v[88:91], v[190:193], v[150:153], v[88:91]
	v_mfma_f32_16x16x32_bf16 v[84:87], v[182:185], v[158:161], v[84:87]
	v_mfma_f32_16x16x32_bf16 v[80:83], v[190:193], v[158:161], v[80:83]
	v_mfma_f32_16x16x32_bf16 v[76:79], v[182:185], v[166:169], v[76:79]
	v_mfma_f32_16x16x32_bf16 v[72:75], v[190:193], v[166:169], v[72:75]
	v_mfma_f32_16x16x32_bf16 v[68:71], v[182:185], v[174:177], v[68:71]
	v_mfma_f32_16x16x32_bf16 v[64:67], v[190:193], v[174:177], v[64:67]
	s_barrier
	ds_read_b128 v[146:149], v230 offset:0
	ds_read_b128 v[150:153], v230 offset:0x400
	ds_read_b128 v[154:157], v230 offset:0x800
	ds_read_b128 v[158:161], v230 offset:0xc00
	ds_read_b128 v[162:165], v230 offset:0x1000
	ds_read_b128 v[166:169], v230 offset:0x1400
	ds_read_b128 v[170:173], v230 offset:0x1800
	s_mov_b64 s[58:59], 0x180
	s_mov_b32 m0, s65
	ds_read_b128 v[174:177], v230 offset:0x1c00
	s_mov_b64 s[58:59], 0x20180
	s_add_u32 s90, s48, 0x180
	s_addc_u32 s91, s49, 0
	global_load_lds_dwordx4 v214, s[90:91]
	v_lshl_add_u64 v[194:195], v[194:195], 0, s[58:59]
	s_mov_b32 m0, s66
	s_nop 0
	s_add_u32 s90, s48, 0x20180
	s_addc_u32 s91, s49, 0
	global_load_lds_dwordx4 v214, s[90:91]
	s_barrier
; #define WAIT_V(n) asm volatile("s_waitcnt vmcnt(%0)" ::"n"(n) : "memory")
; #define SCHED() __builtin_amdgcn_sched_barrier(0)
; #define LGKM(n) asm volatile("s_waitcnt lgkmcnt(%0)" ::"n"(n) : "memory")
; #define STAGE_A(b, h, kt) STAGE_AX(Ag, b, h, kt)
; #define STAGE_B(b, h, kt) STAGE_BX(Bg, b, h, kt)
; #define LDA(b, h) do { const unsigned pa_ = lds0 + SLOTA(b, h) + wr * 8192 + laneoff; _Pragma("unroll") for (int m = 0; m < 4; ++m)   \
;       _Pragma("unroll") for (int k = 0; k < 2; ++k) DSR(At[m][k], pa_, m * 2048 + k * 1024); } while (0)
; #define LDB(dst, b, h) do { const unsigned pb_ = lds0 + SLOTB(b, h) + wc * 4096 + laneoff; _Pragma("unroll") for (int n = 0; n < 2; ++n) \
;       _Pragma("unroll") for (int k = 0; k < 2; ++k) DSR(dst[n][k], pb_, n * 2048 + k * 1024); } while (0)
; #define BAR __builtin_amdgcn_s_barrier()
; #define LGKM(n) asm volatile("s_waitcnt lgkmcnt(%0)" ::"n"(n) : "memory")
; template <int EPI, bool SWP> ...
;     ...
;     STAGE_B(1, 1, t + 3);
;     WAIT_V(6); BAR; SCHED(); MMA(1, 1, B1); BAR; SCHED();
;   }
;   { LDB(B0, 0, 0); LDA(0, 0); STAGE_A(1, 1, nt - 1);
;     BAR; LGKM(0); SCHED(); MMA(0, 0, B0); BAR; SCHED();
;     LDB(B1, 0, 1); BAR; LGKM(0); SCHED(); MMA(0, 1, B1); BAR; SCHED();
;     LDA(0, 1); WAIT_V(4); BAR; LGKM(0); SCHED(); MMA(1, 0, B0); MMA(1, 1, B1); BAR; SCHED(); }
	s_waitcnt lgkmcnt(0)
	v_mfma_f32_16x16x32_bf16 v[60:63], v[130:133], v[146:149], v[60:63]
	v_mfma_f32_16x16x32_bf16 v[56:59], v[138:141], v[146:149], v[56:59]
	v_mfma_f32_16x16x32_bf16 v[52:55], v[130:133], v[154:157], v[52:55]
	v_mfma_f32_16x16x32_bf16 v[48:51], v[138:141], v[154:157], v[48:51]
	v_mfma_f32_16x16x32_bf16 v[44:47], v[130:133], v[162:165], v[44:47]
	v_mfma_f32_16x16x32_bf16 v[40:43], v[138:141], v[162:165], v[40:43]
	v_mfma_f32_16x16x32_bf16 v[36:39], v[130:133], v[170:173], v[36:39]
	v_mfma_f32_16x16x32_bf16 v[32:35], v[138:141], v[170:173], v[32:35]
	v_mfma_f32_16x16x32_bf16 v[60:63], v[134:137], v[150:153], v[60:63]
	v_mfma_f32_16x16x32_bf16 v[56:59], v[142:145], v[150:153], v[56:59]
	v_mfma_f32_16x16x32_bf16 v[52:55], v[134:137], v[158:161], v[52:55]
	v_mfma_f32_16x16x32_bf16 v[48:51], v[142:145], v[158:161], v[48:51]
	v_mfma_f32_16x16x32_bf16 v[44:47], v[134:137], v[166:169], v[44:47]
	v_mfma_f32_16x16x32_bf16 v[40:43], v[142:145], v[166:169], v[40:43]
	v_mfma_f32_16x16x32_bf16 v[36:39], v[134:137], v[174:177], v[36:39]
	v_mfma_f32_16x16x32_bf16 v[32:35], v[142:145], v[174:177], v[32:35]
	s_barrier
	s_mov_b64 s[58:59], 0xe040180
	s_mov_b32 m0, s67
	s_mov_b64 s[58:59], 0xe060180
	s_add_u32 s90, s50, 0xe040180
	s_addc_u32 s91, s51, 0
	global_load_lds_dwordx4 v214, s[90:91]
	s_mov_b32 m0, s68
	s_nop 0
	s_add_u32 s90, s50, 0xe060180
	s_addc_u32 s91, s51, 0
	global_load_lds_dwordx4 v214, s[90:91]
	s_waitcnt vmcnt(6)
	s_barrier
	v_mfma_f32_16x16x32_bf16 v[28:31], v[178:181], v[146:149], v[28:31]
	v_mfma_f32_16x16x32_bf16 v[24:27], v[186:189], v[146:149], v[24:27]
	v_mfma_f32_16x16x32_bf16 v[20:23], v[178:181], v[154:157], v[20:23]
	v_mfma_f32_16x16x32_bf16 v[16:19], v[186:189], v[154:157], v[16:19]
	v_mfma_f32_16x16x32_bf16 v[12:15], v[178:181], v[162:165], v[12:15]
	v_mfma_f32_16x16x32_bf16 v[8:11], v[186:189], v[162:165], v[8:11]
	v_mfma_f32_16x16x32_bf16 v[4:7], v[178:181], v[170:173], v[4:7]
	v_mfma_f32_16x16x32_bf16 v[0:3], v[186:189], v[170:173], v[0:3]
	v_mfma_f32_16x16x32_bf16 v[28:31], v[182:185], v[150:153], v[28:31]
	v_mfma_f32_16x16x32_bf16 v[24:27], v[190:193], v[150:153], v[24:27]
	v_mfma_f32_16x16x32_bf16 v[20:23], v[182:185], v[158:161], v[20:23]
	v_mfma_f32_16x16x32_bf16 v[16:19], v[190:193], v[158:161], v[16:19]
	v_mfma_f32_16x16x32_bf16 v[12:15], v[182:185], v[166:169], v[12:15]
	v_mfma_f32_16x16x32_bf16 v[8:11], v[190:193], v[166:169], v[8:11]
	v_mfma_f32_16x16x32_bf16 v[4:7], v[182:185], v[174:177], v[4:7]
	v_mfma_f32_16x16x32_bf16 v[0:3], v[190:193], v[174:177], v[0:3]
	s_add_i32 s35, s35, 2
	s_add_u32 s50, s50, 0x100
	s_addc_u32 s51, s51, 0
	s_add_u32 s48, s48, 0x100
	s_addc_u32 s49, s49, 0
	s_cmp_gt_u32 s35, 11
	s_barrier
	s_cbranch_scc0 .LBB0_354
	ds_read_b128 v[140:143], v222 offset:0
	ds_read_b128 v[144:147], v222 offset:0x400
	ds_read_b128 v[148:151], v222 offset:0x800
	ds_read_b128 v[152:155], v222 offset:0xc00
	ds_read_b128 v[130:133], v223 offset:0
	ds_read_b128 v[134:137], v223 offset:0x400
	ds_read_b128 v[156:159], v223 offset:0x800
	ds_read_b128 v[160:163], v223 offset:0xc00
	ds_read_b128 v[164:167], v223 offset:0x1000
	ds_read_b128 v[168:171], v223 offset:0x1400
	ds_read_b128 v[172:175], v223 offset:0x1800
	s_mov_b64 s[48:49], 0x40780
	s_mov_b32 m0, s69
	ds_read_b128 v[176:179], v223 offset:0x1c00
	v_lshl_add_u64 v[138:139], v[128:129], 0, s[48:49]
	global_load_lds_dwordx4 v[138:139], off
	v_lshl_add_u64 v[128:129], v[128:129], 0, s[26:27]
	s_mov_b32 m0, s70
	s_ashr_i32 s39, s38, 31
	global_load_lds_dwordx4 v[128:129], off
	s_lshl_b64 s[48:49], s[38:39], 19
	s_add_u32 s48, s56, s48
	s_addc_u32 s49, s57, s49
	s_ashr_i32 s35, s34, 31
	s_barrier
	s_waitcnt lgkmcnt(0)
	s_lshl_b64 s[50:51], s[34:35], 19
	v_readlane_b32 s58, v254, 30
	v_readlane_b32 s59, v254, 31
	s_add_u32 s50, s58, s50
	s_addc_u32 s51, s59, s51
	v_mfma_f32_16x16x32_bf16 v[124:127], v[140:143], v[130:133], v[124:127]
	v_mfma_f32_16x16x32_bf16 v[120:123], v[148:151], v[130:133], v[120:123]
	v_mfma_f32_16x16x32_bf16 v[116:119], v[140:143], v[156:159], v[116:119]
	v_mfma_f32_16x16x32_bf16 v[112:115], v[148:151], v[156:159], v[112:115]
	v_mfma_f32_16x16x32_bf16 v[108:111], v[140:143], v[164:167], v[108:111]
	v_mfma_f32_16x16x32_bf16 v[104:107], v[148:151], v[164:167], v[104:107]
	v_mfma_f32_16x16x32_bf16 v[100:103], v[140:143], v[172:175], v[100:103]
	v_mfma_f32_16x16x32_bf16 v[96:99], v[148:151], v[172:175], v[96:99]
	v_mfma_f32_16x16x32_bf16 v[124:127], v[144:147], v[134:137], v[124:127]
	v_mfma_f32_16x16x32_bf16 v[180:183], v[152:155], v[134:137], v[120:123]
	v_mfma_f32_16x16x32_bf16 v[116:119], v[144:147], v[160:163], v[116:119]
	v_mfma_f32_16x16x32_bf16 v[184:187], v[152:155], v[160:163], v[112:115]
	v_mfma_f32_16x16x32_bf16 v[108:111], v[144:147], v[168:171], v[108:111]
	v_mfma_f32_16x16x32_bf16 v[188:191], v[152:155], v[168:171], v[104:107]
	v_mfma_f32_16x16x32_bf16 v[100:103], v[144:147], v[176:179], v[100:103]
	v_mfma_f32_16x16x32_bf16 v[192:195], v[152:155], v[176:179], v[96:99]
	s_barrier
	ds_read_b128 v[96:99], v224 offset:0
	ds_read_b128 v[104:107], v224 offset:0x400
	ds_read_b128 v[112:115], v224 offset:0x800
	ds_read_b128 v[120:123], v224 offset:0xc00
	s_barrier
; #define WAIT_V(n) asm volatile("s_waitcnt vmcnt(%0)" ::"n"(n) : "memory")
; #define SCHED() __builtin_amdgcn_sched_barrier(0)
; #define LGKM(n) asm volatile("s_waitcnt lgkmcnt(%0)" ::"n"(n) : "memory")
; #define LDA(b, h) do { const unsigned pa_ = lds0 + SLOTA(b, h) + wr * 8192 + laneoff; _Pragma("unroll") for (int m = 0; m < 4; ++m)   \
;       _Pragma("unroll") for (int k = 0; k < 2; ++k) DSR(At[m][k], pa_, m * 2048 + k * 1024); } while (0)
; #define LDB(dst, b, h) do { const unsigned pb_ = lds0 + SLOTB(b, h) + wc * 4096 + laneoff; _Pragma("unroll") for (int n = 0; n < 2; ++n) \
;       _Pragma("unroll") for (int k = 0; k < 2; ++k) DSR(dst[n][k], pb_, n * 2048 + k * 1024); } while (0)
; #define BAR __builtin_amdgcn_s_barrier()
; #define LGKM(n) asm volatile("s_waitcnt lgkmcnt(%0)" ::"n"(n) : "memory")
; template <int EPI, bool SWP> ...
;     ...
;     LDA(0, 1); WAIT_V(4); BAR; LGKM(0); SCHED(); MMA(1, 0, B0); MMA(1, 1, B1); BAR; SCHED(); }
;   { LDB(B0, 1, 0); LDA(1, 0); WAIT_V(2); BAR; LGKM(0); SCHED(); MMA(0, 0, B0); BAR; SCHED();
	s_waitcnt lgkmcnt(0)
	v_mfma_f32_16x16x32_bf16 v[92:95], v[96:99], v[130:133], v[92:95]
	v_mfma_f32_16x16x32_bf16 v[88:91], v[112:115], v[130:133], v[88:91]
	v_mfma_f32_16x16x32_bf16 v[84:87], v[96:99], v[156:159], v[84:87]
	v_mfma_f32_16x16x32_bf16 v[80:83], v[112:115], v[156:159], v[80:83]
	v_mfma_f32_16x16x32_bf16 v[76:79], v[96:99], v[164:167], v[76:79]
	v_mfma_f32_16x16x32_bf16 v[72:75], v[112:115], v[164:167], v[72:75]
	v_mfma_f32_16x16x32_bf16 v[68:71], v[96:99], v[172:175], v[68:71]
	v_mfma_f32_16x16x32_bf16 v[64:67], v[112:115], v[172:175], v[64:67]
	v_mfma_f32_16x16x32_bf16 v[92:95], v[104:107], v[134:137], v[92:95]
	v_mfma_f32_16x16x32_bf16 v[196:199], v[120:123], v[134:137], v[88:91]
	v_mfma_f32_16x16x32_bf16 v[84:87], v[104:107], v[160:163], v[84:87]
	v_mfma_f32_16x16x32_bf16 v[200:203], v[120:123], v[160:163], v[80:83]
	v_mfma_f32_16x16x32_bf16 v[76:79], v[104:107], v[168:171], v[76:79]
	v_mfma_f32_16x16x32_bf16 v[204:207], v[120:123], v[168:171], v[72:75]
	v_mfma_f32_16x16x32_bf16 v[68:71], v[104:107], v[176:179], v[68:71]
	v_mfma_f32_16x16x32_bf16 v[176:179], v[120:123], v[176:179], v[64:67]
	s_barrier
	ds_read_b128 v[64:67], v225 offset:0
	ds_read_b128 v[72:75], v225 offset:0x400
	ds_read_b128 v[80:83], v225 offset:0x800
	ds_read_b128 v[88:91], v225 offset:0xc00
	ds_read_b128 v[156:159], v225 offset:0x1000
	ds_read_b128 v[160:163], v225 offset:0x1400
	ds_read_b128 v[164:167], v225 offset:0x1800
	ds_read_b128 v[168:171], v225 offset:0x1c00
	s_waitcnt vmcnt(4)
	s_barrier
	s_waitcnt lgkmcnt(0)
	v_mfma_f32_16x16x32_bf16 v[60:63], v[140:143], v[64:67], v[60:63]
	v_mfma_f32_16x16x32_bf16 v[56:59], v[148:151], v[64:67], v[56:59]
	v_mfma_f32_16x16x32_bf16 v[52:55], v[140:143], v[80:83], v[52:55]
	v_mfma_f32_16x16x32_bf16 v[48:51], v[148:151], v[80:83], v[48:51]
	v_mfma_f32_16x16x32_bf16 v[44:47], v[140:143], v[156:159], v[44:47]
	v_mfma_f32_16x16x32_bf16 v[40:43], v[148:151], v[156:159], v[40:43]
	v_mfma_f32_16x16x32_bf16 v[36:39], v[140:143], v[164:167], v[36:39]
	v_mfma_f32_16x16x32_bf16 v[32:35], v[148:151], v[164:167], v[32:35]
	v_mfma_f32_16x16x32_bf16 v[60:63], v[144:147], v[72:75], v[60:63]
	v_mfma_f32_16x16x32_bf16 v[128:131], v[152:155], v[72:75], v[56:59]
	v_mfma_f32_16x16x32_bf16 v[52:55], v[144:147], v[88:91], v[52:55]
	v_mfma_f32_16x16x32_bf16 v[132:135], v[152:155], v[88:91], v[48:51]
	v_mfma_f32_16x16x32_bf16 v[44:47], v[144:147], v[160:163], v[44:47]
	v_mfma_f32_16x16x32_bf16 v[136:139], v[152:155], v[160:163], v[40:43]
	v_mfma_f32_16x16x32_bf16 v[36:39], v[144:147], v[168:171], v[36:39]
	v_mfma_f32_16x16x32_bf16 v[140:143], v[152:155], v[168:171], v[32:35]
	v_mfma_f32_16x16x32_bf16 v[28:31], v[96:99], v[64:67], v[28:31]
	v_mfma_f32_16x16x32_bf16 v[24:27], v[112:115], v[64:67], v[24:27]
	v_mfma_f32_16x16x32_bf16 v[20:23], v[96:99], v[80:83], v[20:23]
	v_mfma_f32_16x16x32_bf16 v[16:19], v[112:115], v[80:83], v[16:19]
	v_mfma_f32_16x16x32_bf16 v[12:15], v[96:99], v[156:159], v[12:15]
	v_mfma_f32_16x16x32_bf16 v[8:11], v[112:115], v[156:159], v[8:11]
	v_mfma_f32_16x16x32_bf16 v[4:7], v[96:99], v[164:167], v[4:7]
	v_mfma_f32_16x16x32_bf16 v[0:3], v[112:115], v[164:167], v[0:3]
	v_mfma_f32_16x16x32_bf16 v[28:31], v[104:107], v[72:75], v[28:31]
	v_mfma_f32_16x16x32_bf16 v[144:147], v[120:123], v[72:75], v[24:27]
	v_mfma_f32_16x16x32_bf16 v[20:23], v[104:107], v[88:91], v[20:23]
	v_mfma_f32_16x16x32_bf16 v[148:151], v[120:123], v[88:91], v[16:19]
	v_mfma_f32_16x16x32_bf16 v[12:15], v[104:107], v[160:163], v[12:15]
	v_mfma_f32_16x16x32_bf16 v[152:155], v[120:123], v[160:163], v[8:11]
	v_mfma_f32_16x16x32_bf16 v[4:7], v[104:107], v[168:171], v[4:7]
	v_mfma_f32_16x16x32_bf16 v[156:159], v[120:123], v[168:171], v[0:3]
	s_barrier
	ds_read_b128 v[0:3], v226 offset:0
	ds_read_b128 v[8:11], v226 offset:0x400
	ds_read_b128 v[16:19], v226 offset:0x800
	ds_read_b128 v[24:27], v226 offset:0xc00
	ds_read_b128 v[32:35], v227 offset:0
	ds_read_b128 v[40:43], v227 offset:0x400
	ds_read_b128 v[48:51], v227 offset:0x800
	ds_read_b128 v[56:59], v227 offset:0xc00
	ds_read_b128 v[64:67], v227 offset:0x1000
	ds_read_b128 v[218:221], v227 offset:0x1400
	ds_read_b128 v[236:239], v227 offset:0x1800
	ds_read_b128 v[240:243], v227 offset:0x1c00
	s_waitcnt vmcnt(2)
	s_barrier
; #define WAIT_V(n) asm volatile("s_waitcnt vmcnt(%0)" ::"n"(n) : "memory")
; #define SCHED() __builtin_amdgcn_sched_barrier(0)
; #define LGKM(n) asm volatile("s_waitcnt lgkmcnt(%0)" ::"n"(n) : "memory")
; #define STAGE_AX(AG, b, h, kt) do { _Pragma("unroll") for (int i = 0; i < 2; ++i)                                    \
;       __builtin_amdgcn_global_load_lds((const unsigned*)(((AG) + ((size_t)(kt) * (BK * 2) + (size_t)((h) * 2 + i) * 128 * lda)) + aoff), \
;                                        (unsigned*)(shm + SLOTA(b, h) + wid * 1024 + i * 8192), 16, 0, 0); } while (0)
; #define STAGE_BX(BG, b, h, kt) do { _Pragma("unroll") for (int i = 0; i < 2; ++i)                                    \
;       __builtin_amdgcn_global_load_lds((const unsigned*)(((BG) + ((size_t)(kt) * (BK * 2) + (size_t)((h) * 2 + i) * 128 * K)) + boff),   \
;                                        (unsigned*)(shm + SLOTB(b, h) + wid * 1024 + i * 8192), 16, 0, 0); } while (0)
; #define LDA(b, h) do { const unsigned pa_ = lds0 + SLOTA(b, h) + wr * 8192 + laneoff; _Pragma("unroll") for (int m = 0; m < 4; ++m)   \
;       _Pragma("unroll") for (int k = 0; k < 2; ++k) DSR(At[m][k], pa_, m * 2048 + k * 1024); } while (0)
; #define LDB(dst, b, h) do { const unsigned pb_ = lds0 + SLOTB(b, h) + wc * 4096 + laneoff; _Pragma("unroll") for (int n = 0; n < 2; ++n) \
;       _Pragma("unroll") for (int k = 0; k < 2; ++k) DSR(dst[n][k], pb_, n * 2048 + k * 1024); } while (0)
; #define BAR __builtin_amdgcn_s_barrier()
; #define LGKM(n) asm volatile("s_waitcnt lgkmcnt(%0)" ::"n"(n) : "memory")
; template <int EPI, bool SWP> ...
;     ...
;   { LDB(B0, 1, 0); LDA(1, 0); WAIT_V(2); BAR; LGKM(0); SCHED(); MMA(0, 0, B0); BAR; SCHED();
;     LDB(B1, 1, 1); WAIT_V(0); BAR; LGKM(0); SCHED(); MMA(0, 1, B1); BAR; SCHED();
;     LDA(1, 1);
;     if (has_next) { STAGE_BX(Bg_n, 0, 0, 0); STAGE_AX(Ag_n, 0, 0, 0); STAGE_BX(Bg_n, 0, 1, 0); STAGE_AX(Ag_n, 0, 1, 0); }
;     BAR; LGKM(0); SCHED(); MMA(1, 0, B0); MMA(1, 1, B1); BAR; SCHED(); }
;   if (wr == 0) BAR;
;   if (has_next) {
;     STAGE_BX(Bg_n, 1, 0, 1); STAGE_AX(Ag_n, 1, 0, 1); STAGE_BX(Bg_n, 1, 1, 1);
;     if (e.nss > 0 && tid < 256) s_rstd_n[tid] = rsqrtf(ss_next * (1.f / DM) + 1e-6f);
	s_waitcnt lgkmcnt(0)
	v_mfma_f32_16x16x32_bf16 v[72:75], v[0:3], v[32:35], v[124:127]
	v_mfma_f32_16x16x32_bf16 v[120:123], v[8:11], v[40:43], v[72:75]
	v_mfma_f32_16x16x32_bf16 v[72:75], v[16:19], v[32:35], v[180:183]
	v_mfma_f32_16x16x32_bf16 v[124:127], v[24:27], v[40:43], v[72:75]
	v_mfma_f32_16x16x32_bf16 v[72:75], v[0:3], v[48:51], v[116:119]
	v_mfma_f32_16x16x32_bf16 v[112:115], v[8:11], v[56:59], v[72:75]
	v_mfma_f32_16x16x32_bf16 v[72:75], v[16:19], v[48:51], v[184:187]
	v_mfma_f32_16x16x32_bf16 v[116:119], v[24:27], v[56:59], v[72:75]
	v_mfma_f32_16x16x32_bf16 v[72:75], v[0:3], v[64:67], v[108:111]
	v_mfma_f32_16x16x32_bf16 v[104:107], v[8:11], v[218:221], v[72:75]
	v_mfma_f32_16x16x32_bf16 v[72:75], v[16:19], v[64:67], v[188:191]
	v_mfma_f32_16x16x32_bf16 v[108:111], v[24:27], v[218:221], v[72:75]
	v_mfma_f32_16x16x32_bf16 v[72:75], v[0:3], v[236:239], v[100:103]
	v_mfma_f32_16x16x32_bf16 v[96:99], v[8:11], v[240:243], v[72:75]
	v_mfma_f32_16x16x32_bf16 v[72:75], v[16:19], v[236:239], v[192:195]
	v_mfma_f32_16x16x32_bf16 v[100:103], v[24:27], v[240:243], v[72:75]
	s_barrier
	ds_read_b128 v[160:163], v229 offset:0
	ds_read_b128 v[164:167], v229 offset:0x400
	ds_read_b128 v[168:171], v229 offset:0x800
	ds_read_b128 v[172:175], v229 offset:0xc00
	s_waitcnt vmcnt(0)
	s_barrier
	s_waitcnt lgkmcnt(0)
	v_mfma_f32_16x16x32_bf16 v[72:75], v[160:163], v[32:35], v[92:95]
	v_mfma_f32_16x16x32_bf16 v[32:35], v[168:171], v[32:35], v[196:199]
	v_mfma_f32_16x16x32_bf16 v[92:95], v[172:175], v[40:43], v[32:35]
	v_mfma_f32_16x16x32_bf16 v[32:35], v[160:163], v[48:51], v[84:87]
	v_mfma_f32_16x16x32_bf16 v[80:83], v[164:167], v[56:59], v[32:35]
	v_mfma_f32_16x16x32_bf16 v[32:35], v[168:171], v[48:51], v[200:203]
	v_mfma_f32_16x16x32_bf16 v[84:87], v[172:175], v[56:59], v[32:35]
	v_mfma_f32_16x16x32_bf16 v[32:35], v[160:163], v[64:67], v[76:79]
	v_mfma_f32_16x16x32_bf16 v[88:91], v[164:167], v[40:43], v[72:75]
	v_mfma_f32_16x16x32_bf16 v[72:75], v[164:167], v[218:221], v[32:35]
	v_mfma_f32_16x16x32_bf16 v[32:35], v[168:171], v[64:67], v[204:207]
	v_mfma_f32_16x16x32_bf16 v[76:79], v[172:175], v[218:221], v[32:35]
	v_mfma_f32_16x16x32_bf16 v[32:35], v[160:163], v[236:239], v[68:71]
	v_mfma_f32_16x16x32_bf16 v[64:67], v[164:167], v[240:243], v[32:35]
	v_mfma_f32_16x16x32_bf16 v[32:35], v[168:171], v[236:239], v[176:179]
	v_mfma_f32_16x16x32_bf16 v[68:71], v[172:175], v[240:243], v[32:35]
	s_barrier
	ds_read_b128 v[200:203], v230 offset:0
	ds_read_b128 v[204:207], v230 offset:0x400
	ds_read_b128 v[192:195], v230 offset:0x800
	ds_read_b128 v[196:199], v230 offset:0xc00
	ds_read_b128 v[184:187], v230 offset:0x1000
	ds_read_b128 v[188:191], v230 offset:0x1400
	ds_read_b128 v[176:179], v230 offset:0x1800
	ds_read_b128 v[180:183], v230 offset:0x1c00
	s_and_b64 vcc, exec, s[44:45]
	v_lshl_add_u64 v[218:219], s[50:51], 0, v[208:209]
	v_lshl_add_u64 v[220:221], s[48:49], 0, v[208:209]
	s_cbranch_vccz .LBB0_357
	s_mov_b32 m0, s16
	v_lshl_add_u64 v[32:33], v[218:219], 0, s[4:5]
	global_load_lds_dwordx4 v[218:219], off
	s_mov_b32 m0, s17
	s_nop 0
	global_load_lds_dwordx4 v[32:33], off
	s_mov_b32 m0, s3
	v_lshl_add_u64 v[32:33], v[220:221], 0, s[4:5]
	global_load_lds_dwordx4 v[220:221], off
	s_mov_b32 m0, s18
	s_nop 0
	global_load_lds_dwordx4 v[32:33], off
	v_lshl_add_u64 v[32:33], v[218:219], 0, s[10:11]
	s_mov_b32 m0, s19
	s_nop 0
	global_load_lds_dwordx4 v[32:33], off
	v_lshl_add_u64 v[32:33], v[218:219], 0, s[12:13]
	s_mov_b32 m0, s60
	s_nop 0
	global_load_lds_dwordx4 v[32:33], off
	v_lshl_add_u64 v[32:33], v[220:221], 0, s[10:11]
	s_mov_b32 m0, s61
	s_nop 0
	global_load_lds_dwordx4 v[32:33], off
	v_lshl_add_u64 v[32:33], v[220:221], 0, s[12:13]
	s_mov_b32 m0, s62
	s_nop 0
	global_load_lds_dwordx4 v[32:33], off

; #define WAIT_V(n) asm volatile("s_waitcnt vmcnt(%0)" ::"n"(n) : "memory")
; #define SCHED() __builtin_amdgcn_sched_barrier(0)
; #define LGKM(n) asm volatile("s_waitcnt lgkmcnt(%0)" ::"n"(n) : "memory")
; #define STAGE_A(b, h, kt) STAGE_AX(Ag, b, h, kt)
; #define STAGE_B(b, h, kt) STAGE_BX(Bg, b, h, kt)
; #define LDA(b, h) do { const unsigned pa_ = lds0 + SLOTA(b, h) + wr * 8192 + laneoff; _Pragma("unroll") for (int m = 0; m < 4; ++m)   \
;       _Pragma("unroll") for (int k = 0; k < 2; ++k) DSR(At[m][k], pa_, m * 2048 + k * 1024); } while (0)
; #define LDB(dst, b, h) do { const unsigned pb_ = lds0 + SLOTB(b, h) + wc * 4096 + laneoff; _Pragma("unroll") for (int n = 0; n < 2; ++n) \
;       _Pragma("unroll") for (int k = 0; k < 2; ++k) DSR(dst[n][k], pb_, n * 2048 + k * 1024); } while (0)
; #define BAR __builtin_amdgcn_s_barrier()
; #define LGKM(n) asm volatile("s_waitcnt lgkmcnt(%0)" ::"n"(n) : "memory")
; template <int EPI, bool SWP> ...
;     ...
;   for (int t = 0; t < nt - 2; t += 2) {
;     LDB(B0, 0, 0); LDA(0, 0); STAGE_A(1, 1, t + 1);
;     LGKM(8); BAR; LGKM(0); SCHED(); MMA(0, 0, B0); BAR; SCHED();
;     LDB(B1, 0, 1); STAGE_B(0, 0, t + 2);
;     BAR; LGKM(0); SCHED(); MMA(0, 1, B1); BAR; SCHED();
;     LDA(0, 1); STAGE_A(0, 0, t + 2);
;     BAR; LGKM(0); SCHED(); MMA(1, 0, B0); BAR; SCHED();
;     STAGE_B(0, 1, t + 2);
;     WAIT_V(6); BAR; SCHED(); MMA(1, 1, B1); BAR; SCHED();
.LBB0_385:
	ds_read_b128 v[130:133], v224 offset:0
	ds_read_b128 v[134:137], v224 offset:0x400
	ds_read_b128 v[138:141], v224 offset:0x800
	ds_read_b128 v[142:145], v224 offset:0xc00
	ds_read_b128 v[146:149], v225 offset:0
	ds_read_b128 v[150:153], v225 offset:0x400
	ds_read_b128 v[154:157], v225 offset:0x800
	ds_read_b128 v[158:161], v225 offset:0xc00
	ds_read_b128 v[162:165], v225 offset:0x1000
	ds_read_b128 v[166:169], v225 offset:0x1400
	ds_read_b128 v[170:173], v225 offset:0x1800
	v_lshl_add_u64 v[194:195], s[50:51], 0, v[218:219]
	s_mov_b64 s[58:59], 0xf140080
	s_mov_b32 m0, s69
	ds_read_b128 v[174:177], v225 offset:0x1c00
	s_mov_b64 s[58:59], 0xf160080
	s_add_u32 s90, s50, 0xf140080
	s_addc_u32 s91, s51, 0
	global_load_lds_dwordx4 v218, s[90:91]
	s_mov_b32 m0, s70
	s_nop 0
	s_add_u32 s90, s50, 0xf160080
	s_addc_u32 s91, s51, 0
	global_load_lds_dwordx4 v218, s[90:91]
	s_waitcnt lgkmcnt(8)
	s_barrier
	s_waitcnt lgkmcnt(0)
	v_mfma_f32_16x16x32_bf16 v[124:127], v[130:133], v[146:149], v[124:127]
	v_mfma_f32_16x16x32_bf16 v[120:123], v[138:141], v[146:149], v[120:123]
	v_mfma_f32_16x16x32_bf16 v[116:119], v[130:133], v[154:157], v[116:119]
	v_mfma_f32_16x16x32_bf16 v[112:115], v[138:141], v[154:157], v[112:115]
	v_mfma_f32_16x16x32_bf16 v[108:111], v[130:133], v[162:165], v[108:111]
	v_mfma_f32_16x16x32_bf16 v[104:107], v[138:141], v[162:165], v[104:107]
	v_mfma_f32_16x16x32_bf16 v[100:103], v[130:133], v[170:173], v[100:103]
	v_mfma_f32_16x16x32_bf16 v[96:99], v[138:141], v[170:173], v[96:99]
	v_mfma_f32_16x16x32_bf16 v[124:127], v[134:137], v[150:153], v[124:127]
	v_mfma_f32_16x16x32_bf16 v[120:123], v[142:145], v[150:153], v[120:123]
	v_mfma_f32_16x16x32_bf16 v[116:119], v[134:137], v[158:161], v[116:119]
	v_mfma_f32_16x16x32_bf16 v[112:115], v[142:145], v[158:161], v[112:115]
	v_mfma_f32_16x16x32_bf16 v[108:111], v[134:137], v[166:169], v[108:111]
	v_mfma_f32_16x16x32_bf16 v[104:107], v[142:145], v[166:169], v[104:107]
	v_mfma_f32_16x16x32_bf16 v[100:103], v[134:137], v[174:177], v[100:103]
	v_mfma_f32_16x16x32_bf16 v[96:99], v[142:145], v[174:177], v[96:99]
	s_barrier
	ds_read_b128 v[178:181], v226 offset:0
	ds_read_b128 v[182:185], v226 offset:0x400
	ds_read_b128 v[186:189], v226 offset:0x800
	v_lshl_add_u64 v[196:197], s[48:49], 0, v[218:219]
	s_mov_b64 s[58:59], 0xe400100
	s_mov_b32 m0, s16
	ds_read_b128 v[190:193], v226 offset:0xc00
	s_mov_b64 s[58:59], 0xe420100
	s_add_u32 s90, s48, 0xe400100
	s_addc_u32 s91, s49, 0
	global_load_lds_dwordx4 v218, s[90:91]
	s_mov_b32 m0, s17
	s_nop 0
	s_add_u32 s90, s48, 0xe420100
	s_addc_u32 s91, s49, 0
	global_load_lds_dwordx4 v218, s[90:91]
	s_barrier
	s_waitcnt lgkmcnt(0)
	v_mfma_f32_16x16x32_bf16 v[92:95], v[178:181], v[146:149], v[92:95]
	v_mfma_f32_16x16x32_bf16 v[88:91], v[186:189], v[146:149], v[88:91]
	v_mfma_f32_16x16x32_bf16 v[84:87], v[178:181], v[154:157], v[84:87]
	v_mfma_f32_16x16x32_bf16 v[80:83], v[186:189], v[154:157], v[80:83]
	v_mfma_f32_16x16x32_bf16 v[76:79], v[178:181], v[162:165], v[76:79]
	v_mfma_f32_16x16x32_bf16 v[72:75], v[186:189], v[162:165], v[72:75]
	v_mfma_f32_16x16x32_bf16 v[68:71], v[178:181], v[170:173], v[68:71]
	v_mfma_f32_16x16x32_bf16 v[64:67], v[186:189], v[170:173], v[64:67]
	v_mfma_f32_16x16x32_bf16 v[92:95], v[182:185], v[150:153], v[92:95]
	v_mfma_f32_16x16x32_bf16 v[88:91], v[190:193], v[150:153], v[88:91]
	v_mfma_f32_16x16x32_bf16 v[84:87], v[182:185], v[158:161], v[84:87]
	v_mfma_f32_16x16x32_bf16 v[80:83], v[190:193], v[158:161], v[80:83]
	v_mfma_f32_16x16x32_bf16 v[76:79], v[182:185], v[166:169], v[76:79]
	v_mfma_f32_16x16x32_bf16 v[72:75], v[190:193], v[166:169], v[72:75]
	v_mfma_f32_16x16x32_bf16 v[68:71], v[182:185], v[174:177], v[68:71]
	v_mfma_f32_16x16x32_bf16 v[64:67], v[190:193], v[174:177], v[64:67]
	s_barrier
	ds_read_b128 v[146:149], v227 offset:0
	ds_read_b128 v[150:153], v227 offset:0x400
	ds_read_b128 v[154:157], v227 offset:0x800
	ds_read_b128 v[158:161], v227 offset:0xc00
	ds_read_b128 v[162:165], v227 offset:0x1000
	ds_read_b128 v[166:169], v227 offset:0x1400
	ds_read_b128 v[170:173], v227 offset:0x1800
	s_mov_b64 s[58:59], 0xf100100
	s_mov_b32 m0, s3
	ds_read_b128 v[174:177], v227 offset:0x1c00
	s_mov_b64 s[58:59], 0xf120100
	s_add_u32 s90, s50, 0xf100100
	s_addc_u32 s91, s51, 0
	global_load_lds_dwordx4 v218, s[90:91]
	s_mov_b32 m0, s18
	s_nop 0
	s_add_u32 s90, s50, 0xf120100
	s_addc_u32 s91, s51, 0
	global_load_lds_dwordx4 v218, s[90:91]
	s_barrier
	s_waitcnt lgkmcnt(0)
	v_mfma_f32_16x16x32_bf16 v[60:63], v[130:133], v[146:149], v[60:63]
	v_mfma_f32_16x16x32_bf16 v[56:59], v[138:141], v[146:149], v[56:59]
	v_mfma_f32_16x16x32_bf16 v[52:55], v[130:133], v[154:157], v[52:55]
	v_mfma_f32_16x16x32_bf16 v[48:51], v[138:141], v[154:157], v[48:51]
	v_mfma_f32_16x16x32_bf16 v[44:47], v[130:133], v[162:165], v[44:47]
	v_mfma_f32_16x16x32_bf16 v[40:43], v[138:141], v[162:165], v[40:43]
	v_mfma_f32_16x16x32_bf16 v[36:39], v[130:133], v[170:173], v[36:39]
	v_mfma_f32_16x16x32_bf16 v[32:35], v[138:141], v[170:173], v[32:35]
	v_mfma_f32_16x16x32_bf16 v[60:63], v[134:137], v[150:153], v[60:63]
	v_mfma_f32_16x16x32_bf16 v[56:59], v[142:145], v[150:153], v[56:59]
	v_mfma_f32_16x16x32_bf16 v[52:55], v[134:137], v[158:161], v[52:55]
	v_mfma_f32_16x16x32_bf16 v[48:51], v[142:145], v[158:161], v[48:51]
	v_mfma_f32_16x16x32_bf16 v[44:47], v[134:137], v[166:169], v[44:47]
	v_mfma_f32_16x16x32_bf16 v[40:43], v[142:145], v[166:169], v[40:43]
	v_mfma_f32_16x16x32_bf16 v[36:39], v[134:137], v[174:177], v[36:39]
	v_mfma_f32_16x16x32_bf16 v[32:35], v[142:145], v[174:177], v[32:35]
	s_barrier
; #define WAIT_V(n) asm volatile("s_waitcnt vmcnt(%0)" ::"n"(n) : "memory")
; #define SCHED() __builtin_amdgcn_sched_barrier(0)
; #define LGKM(n) asm volatile("s_waitcnt lgkmcnt(%0)" ::"n"(n) : "memory")
; #define STAGE_A(b, h, kt) STAGE_AX(Ag, b, h, kt)
; #define STAGE_B(b, h, kt) STAGE_BX(Bg, b, h, kt)
; #define LDA(b, h) do { const unsigned pa_ = lds0 + SLOTA(b, h) + wr * 8192 + laneoff; _Pragma("unroll") for (int m = 0; m < 4; ++m)   \
;       _Pragma("unroll") for (int k = 0; k < 2; ++k) DSR(At[m][k], pa_, m * 2048 + k * 1024); } while (0)
; #define LDB(dst, b, h) do { const unsigned pb_ = lds0 + SLOTB(b, h) + wc * 4096 + laneoff; _Pragma("unroll") for (int n = 0; n < 2; ++n) \
;       _Pragma("unroll") for (int k = 0; k < 2; ++k) DSR(dst[n][k], pb_, n * 2048 + k * 1024); } while (0)
; #define BAR __builtin_amdgcn_s_barrier()
; #define LGKM(n) asm volatile("s_waitcnt lgkmcnt(%0)" ::"n"(n) : "memory")
; template <int EPI, bool SWP> ...
;     ...
;     WAIT_V(6); BAR; SCHED(); MMA(1, 1, B1); BAR; SCHED();
;     LDB(B0, 1, 0); LDA(1, 0); STAGE_A(0, 1, t + 2);
;     LGKM(8); BAR; LGKM(0); SCHED(); MMA(0, 0, B0); BAR; SCHED();
;     LDB(B1, 1, 1); STAGE_B(1, 0, t + 3);
;     BAR; LGKM(0); SCHED(); MMA(0, 1, B1); BAR; SCHED();
;     LDA(1, 1); STAGE_A(1, 0, t + 3);
;     BAR; LGKM(0); SCHED(); MMA(1, 0, B0); BAR; SCHED();
	s_mov_b64 s[58:59], 0xe440100
	s_mov_b32 m0, s19
	s_mov_b64 s[58:59], 0xe460100
	s_add_u32 s90, s48, 0xe440100
	s_addc_u32 s91, s49, 0
	global_load_lds_dwordx4 v218, s[90:91]
	s_mov_b32 m0, s60
	s_nop 0
	s_add_u32 s90, s48, 0xe460100
	s_addc_u32 s91, s49, 0
	global_load_lds_dwordx4 v218, s[90:91]
	s_waitcnt vmcnt(6)
	s_barrier
	v_mfma_f32_16x16x32_bf16 v[28:31], v[178:181], v[146:149], v[28:31]
	v_mfma_f32_16x16x32_bf16 v[24:27], v[186:189], v[146:149], v[24:27]
	v_mfma_f32_16x16x32_bf16 v[20:23], v[178:181], v[154:157], v[20:23]
	v_mfma_f32_16x16x32_bf16 v[16:19], v[186:189], v[154:157], v[16:19]
	v_mfma_f32_16x16x32_bf16 v[12:15], v[178:181], v[162:165], v[12:15]
	v_mfma_f32_16x16x32_bf16 v[8:11], v[186:189], v[162:165], v[8:11]
	v_mfma_f32_16x16x32_bf16 v[4:7], v[178:181], v[170:173], v[4:7]
	v_mfma_f32_16x16x32_bf16 v[0:3], v[186:189], v[170:173], v[0:3]
	v_mfma_f32_16x16x32_bf16 v[28:31], v[182:185], v[150:153], v[28:31]
	v_mfma_f32_16x16x32_bf16 v[24:27], v[190:193], v[150:153], v[24:27]
	v_mfma_f32_16x16x32_bf16 v[20:23], v[182:185], v[158:161], v[20:23]
	v_mfma_f32_16x16x32_bf16 v[16:19], v[190:193], v[158:161], v[16:19]
	v_mfma_f32_16x16x32_bf16 v[12:15], v[182:185], v[166:169], v[12:15]
	v_mfma_f32_16x16x32_bf16 v[8:11], v[190:193], v[166:169], v[8:11]
	v_mfma_f32_16x16x32_bf16 v[4:7], v[182:185], v[174:177], v[4:7]
	v_mfma_f32_16x16x32_bf16 v[0:3], v[190:193], v[174:177], v[0:3]
	s_barrier
	ds_read_b128 v[130:133], v229 offset:0
	ds_read_b128 v[134:137], v229 offset:0x400
	ds_read_b128 v[138:141], v229 offset:0x800
	ds_read_b128 v[142:145], v229 offset:0xc00
	ds_read_b128 v[146:149], v230 offset:0
	ds_read_b128 v[150:153], v230 offset:0x400
	ds_read_b128 v[154:157], v230 offset:0x800
	ds_read_b128 v[158:161], v230 offset:0xc00
	ds_read_b128 v[162:165], v230 offset:0x1000
	ds_read_b128 v[166:169], v230 offset:0x1400
	ds_read_b128 v[170:173], v230 offset:0x1800
	s_mov_b64 s[58:59], 0xf140100
	s_mov_b32 m0, s61
	ds_read_b128 v[174:177], v230 offset:0x1c00
	s_mov_b64 s[58:59], 0xf160100
	s_add_u32 s90, s50, 0xf140100
	s_addc_u32 s91, s51, 0
	global_load_lds_dwordx4 v218, s[90:91]
	s_mov_b32 m0, s62
	s_nop 0
	s_add_u32 s90, s50, 0xf160100
	s_addc_u32 s91, s51, 0
	global_load_lds_dwordx4 v218, s[90:91]
	s_waitcnt lgkmcnt(8)
	s_barrier
	s_waitcnt lgkmcnt(0)
	v_mfma_f32_16x16x32_bf16 v[124:127], v[130:133], v[146:149], v[124:127]
	v_mfma_f32_16x16x32_bf16 v[120:123], v[138:141], v[146:149], v[120:123]
	v_mfma_f32_16x16x32_bf16 v[116:119], v[130:133], v[154:157], v[116:119]
	v_mfma_f32_16x16x32_bf16 v[112:115], v[138:141], v[154:157], v[112:115]
	v_mfma_f32_16x16x32_bf16 v[108:111], v[130:133], v[162:165], v[108:111]
	v_mfma_f32_16x16x32_bf16 v[104:107], v[138:141], v[162:165], v[104:107]
	v_mfma_f32_16x16x32_bf16 v[100:103], v[130:133], v[170:173], v[100:103]
	v_mfma_f32_16x16x32_bf16 v[96:99], v[138:141], v[170:173], v[96:99]
	v_mfma_f32_16x16x32_bf16 v[124:127], v[134:137], v[150:153], v[124:127]
	v_mfma_f32_16x16x32_bf16 v[120:123], v[142:145], v[150:153], v[120:123]
	v_mfma_f32_16x16x32_bf16 v[116:119], v[134:137], v[158:161], v[116:119]
	v_mfma_f32_16x16x32_bf16 v[112:115], v[142:145], v[158:161], v[112:115]
	v_mfma_f32_16x16x32_bf16 v[108:111], v[134:137], v[166:169], v[108:111]
	v_mfma_f32_16x16x32_bf16 v[104:107], v[142:145], v[166:169], v[104:107]
	v_mfma_f32_16x16x32_bf16 v[100:103], v[134:137], v[174:177], v[100:103]
	v_mfma_f32_16x16x32_bf16 v[96:99], v[142:145], v[174:177], v[96:99]
	s_barrier
	ds_read_b128 v[178:181], v231 offset:0
	ds_read_b128 v[182:185], v231 offset:0x400
	ds_read_b128 v[186:189], v231 offset:0x800
	s_mov_b64 s[58:59], 0xe400180
	s_mov_b32 m0, s63
	ds_read_b128 v[190:193], v231 offset:0xc00
	s_mov_b64 s[58:59], 0xe420180
	s_add_u32 s90, s48, 0xe400180
	s_addc_u32 s91, s49, 0
	global_load_lds_dwordx4 v218, s[90:91]
	s_mov_b32 m0, s64
	s_nop 0
	s_add_u32 s90, s48, 0xe420180
	s_addc_u32 s91, s49, 0
	global_load_lds_dwordx4 v218, s[90:91]
	s_barrier
	s_waitcnt lgkmcnt(0)
	v_mfma_f32_16x16x32_bf16 v[92:95], v[178:181], v[146:149], v[92:95]
	v_mfma_f32_16x16x32_bf16 v[88:91], v[186:189], v[146:149], v[88:91]
	v_mfma_f32_16x16x32_bf16 v[84:87], v[178:181], v[154:157], v[84:87]
	v_mfma_f32_16x16x32_bf16 v[80:83], v[186:189], v[154:157], v[80:83]
	v_mfma_f32_16x16x32_bf16 v[76:79], v[178:181], v[162:165], v[76:79]
	v_mfma_f32_16x16x32_bf16 v[72:75], v[186:189], v[162:165], v[72:75]
	v_mfma_f32_16x16x32_bf16 v[68:71], v[178:181], v[170:173], v[68:71]
	v_mfma_f32_16x16x32_bf16 v[64:67], v[186:189], v[170:173], v[64:67]
	v_mfma_f32_16x16x32_bf16 v[92:95], v[182:185], v[150:153], v[92:95]
	v_mfma_f32_16x16x32_bf16 v[88:91], v[190:193], v[150:153], v[88:91]
	v_mfma_f32_16x16x32_bf16 v[84:87], v[182:185], v[158:161], v[84:87]
	v_mfma_f32_16x16x32_bf16 v[80:83], v[190:193], v[158:161], v[80:83]
	v_mfma_f32_16x16x32_bf16 v[76:79], v[182:185], v[166:169], v[76:79]
	v_mfma_f32_16x16x32_bf16 v[72:75], v[190:193], v[166:169], v[72:75]
	v_mfma_f32_16x16x32_bf16 v[68:71], v[182:185], v[174:177], v[68:71]
	v_mfma_f32_16x16x32_bf16 v[64:67], v[190:193], v[174:177], v[64:67]
	s_barrier
	ds_read_b128 v[146:149], v232 offset:0
	ds_read_b128 v[150:153], v232 offset:0x400
	ds_read_b128 v[154:157], v232 offset:0x800
	ds_read_b128 v[158:161], v232 offset:0xc00
	ds_read_b128 v[162:165], v232 offset:0x1000
	ds_read_b128 v[166:169], v232 offset:0x1400
	ds_read_b128 v[170:173], v232 offset:0x1800
	s_mov_b64 s[58:59], 0xf100180
	s_mov_b32 m0, s65
	ds_read_b128 v[174:177], v232 offset:0x1c00
	s_mov_b64 s[58:59], 0xf120180
	s_add_u32 s90, s50, 0xf100180
	s_addc_u32 s91, s51, 0
	global_load_lds_dwordx4 v218, s[90:91]
	v_lshl_add_u64 v[194:195], v[194:195], 0, s[58:59]
	s_mov_b32 m0, s66
	s_nop 0
	s_add_u32 s90, s50, 0xf120180
	s_addc_u32 s91, s51, 0
	global_load_lds_dwordx4 v218, s[90:91]
	s_barrier
; #define WAIT_V(n) asm volatile("s_waitcnt vmcnt(%0)" ::"n"(n) : "memory")
; #define SCHED() __builtin_amdgcn_sched_barrier(0)
; #define LGKM(n) asm volatile("s_waitcnt lgkmcnt(%0)" ::"n"(n) : "memory")
; #define STAGE_A(b, h, kt) STAGE_AX(Ag, b, h, kt)
; #define STAGE_B(b, h, kt) STAGE_BX(Bg, b, h, kt)
; #define LDA(b, h) do { const unsigned pa_ = lds0 + SLOTA(b, h) + wr * 8192 + laneoff; _Pragma("unroll") for (int m = 0; m < 4; ++m)   \
;       _Pragma("unroll") for (int k = 0; k < 2; ++k) DSR(At[m][k], pa_, m * 2048 + k * 1024); } while (0)
; #define LDB(dst, b, h) do { const unsigned pb_ = lds0 + SLOTB(b, h) + wc * 4096 + laneoff; _Pragma("unroll") for (int n = 0; n < 2; ++n) \
;       _Pragma("unroll") for (int k = 0; k < 2; ++k) DSR(dst[n][k], pb_, n * 2048 + k * 1024); } while (0)
; #define BAR __builtin_amdgcn_s_barrier()
; #define LGKM(n) asm volatile("s_waitcnt lgkmcnt(%0)" ::"n"(n) : "memory")
; template <int EPI, bool SWP> ...
;     ...
;     STAGE_B(1, 1, t + 3);
;     WAIT_V(6); BAR; SCHED(); MMA(1, 1, B1); BAR; SCHED();
;   }
;   { LDB(B0, 0, 0); LDA(0, 0); STAGE_A(1, 1, nt - 1);
;     BAR; LGKM(0); SCHED(); MMA(0, 0, B0); BAR; SCHED();
;     LDB(B1, 0, 1); BAR; LGKM(0); SCHED(); MMA(0, 1, B1); BAR; SCHED();
;     LDA(0, 1); WAIT_V(4); BAR; LGKM(0); SCHED(); MMA(1, 0, B0); MMA(1, 1, B1); BAR; SCHED(); }
	s_waitcnt lgkmcnt(0)
	v_mfma_f32_16x16x32_bf16 v[60:63], v[130:133], v[146:149], v[60:63]
	v_mfma_f32_16x16x32_bf16 v[56:59], v[138:141], v[146:149], v[56:59]
	v_mfma_f32_16x16x32_bf16 v[52:55], v[130:133], v[154:157], v[52:55]
	v_mfma_f32_16x16x32_bf16 v[48:51], v[138:141], v[154:157], v[48:51]
	v_mfma_f32_16x16x32_bf16 v[44:47], v[130:133], v[162:165], v[44:47]
	v_mfma_f32_16x16x32_bf16 v[40:43], v[138:141], v[162:165], v[40:43]
	v_mfma_f32_16x16x32_bf16 v[36:39], v[130:133], v[170:173], v[36:39]
	v_mfma_f32_16x16x32_bf16 v[32:35], v[138:141], v[170:173], v[32:35]
	v_mfma_f32_16x16x32_bf16 v[60:63], v[134:137], v[150:153], v[60:63]
	v_mfma_f32_16x16x32_bf16 v[56:59], v[142:145], v[150:153], v[56:59]
	v_mfma_f32_16x16x32_bf16 v[52:55], v[134:137], v[158:161], v[52:55]
	v_mfma_f32_16x16x32_bf16 v[48:51], v[142:145], v[158:161], v[48:51]
	v_mfma_f32_16x16x32_bf16 v[44:47], v[134:137], v[166:169], v[44:47]
	v_mfma_f32_16x16x32_bf16 v[40:43], v[142:145], v[166:169], v[40:43]
	v_mfma_f32_16x16x32_bf16 v[36:39], v[134:137], v[174:177], v[36:39]
	v_mfma_f32_16x16x32_bf16 v[32:35], v[142:145], v[174:177], v[32:35]
	s_barrier
	s_mov_b64 s[58:59], 0xe440180
	s_mov_b32 m0, s67
	s_mov_b64 s[58:59], 0xe460180
	s_add_u32 s90, s48, 0xe440180
	s_addc_u32 s91, s49, 0
	global_load_lds_dwordx4 v218, s[90:91]
	s_mov_b32 m0, s68
	s_nop 0
	s_add_u32 s90, s48, 0xe460180
	s_addc_u32 s91, s49, 0
	global_load_lds_dwordx4 v218, s[90:91]
	s_waitcnt vmcnt(6)
	s_barrier
	v_mfma_f32_16x16x32_bf16 v[28:31], v[178:181], v[146:149], v[28:31]
	v_mfma_f32_16x16x32_bf16 v[24:27], v[186:189], v[146:149], v[24:27]
	v_mfma_f32_16x16x32_bf16 v[20:23], v[178:181], v[154:157], v[20:23]
	v_mfma_f32_16x16x32_bf16 v[16:19], v[186:189], v[154:157], v[16:19]
	v_mfma_f32_16x16x32_bf16 v[12:15], v[178:181], v[162:165], v[12:15]
	v_mfma_f32_16x16x32_bf16 v[8:11], v[186:189], v[162:165], v[8:11]
	v_mfma_f32_16x16x32_bf16 v[4:7], v[178:181], v[170:173], v[4:7]
	v_mfma_f32_16x16x32_bf16 v[0:3], v[186:189], v[170:173], v[0:3]
	v_mfma_f32_16x16x32_bf16 v[28:31], v[182:185], v[150:153], v[28:31]
	v_mfma_f32_16x16x32_bf16 v[24:27], v[190:193], v[150:153], v[24:27]
	v_mfma_f32_16x16x32_bf16 v[20:23], v[182:185], v[158:161], v[20:23]
	v_mfma_f32_16x16x32_bf16 v[16:19], v[190:193], v[158:161], v[16:19]
	v_mfma_f32_16x16x32_bf16 v[12:15], v[182:185], v[166:169], v[12:15]
	v_mfma_f32_16x16x32_bf16 v[8:11], v[190:193], v[166:169], v[8:11]
	v_mfma_f32_16x16x32_bf16 v[4:7], v[182:185], v[174:177], v[4:7]
	v_mfma_f32_16x16x32_bf16 v[0:3], v[190:193], v[174:177], v[0:3]
	s_add_i32 s35, s35, 2
	s_add_u32 s48, s48, 0x100
	s_addc_u32 s49, s49, 0
	s_add_u32 s50, s50, 0x100
	s_addc_u32 s51, s51, 0
	s_cmp_gt_u32 s35, 11
	s_barrier
	s_cbranch_scc0 .LBB0_385
	ds_read_b128 v[140:143], v224 offset:0
	ds_read_b128 v[144:147], v224 offset:0x400
	ds_read_b128 v[148:151], v224 offset:0x800
	ds_read_b128 v[152:155], v224 offset:0xc00
	ds_read_b128 v[130:133], v225 offset:0
	ds_read_b128 v[134:137], v225 offset:0x400
	ds_read_b128 v[156:159], v225 offset:0x800
	ds_read_b128 v[160:163], v225 offset:0xc00
	ds_read_b128 v[164:167], v225 offset:0x1000
	ds_read_b128 v[168:171], v225 offset:0x1400
	ds_read_b128 v[172:175], v225 offset:0x1800
	s_mov_b32 m0, s69
	ds_read_b128 v[176:179], v225 offset:0x1c00
	v_lshl_add_u64 v[138:139], v[128:129], 0, s[24:25]
	global_load_lds_dwordx4 v[138:139], off
	v_lshl_add_u64 v[128:129], v[128:129], 0, s[26:27]
	s_mov_b32 m0, s70
	s_ashr_i32 s39, s38, 31
	global_load_lds_dwordx4 v[128:129], off
	s_lshl_b64 s[48:49], s[38:39], 19
	s_add_u32 s48, s46, s48
	s_addc_u32 s49, s47, s49
	s_ashr_i32 s35, s34, 31
	s_barrier
	s_waitcnt lgkmcnt(0)
	s_lshl_b64 s[50:51], s[34:35], 19
	v_readlane_b32 s58, v254, 32
	v_readlane_b32 s59, v254, 33
	s_add_u32 s50, s58, s50
	s_addc_u32 s51, s59, s51
	v_mfma_f32_16x16x32_bf16 v[124:127], v[140:143], v[130:133], v[124:127]
	v_mfma_f32_16x16x32_bf16 v[120:123], v[148:151], v[130:133], v[120:123]
	v_mfma_f32_16x16x32_bf16 v[116:119], v[140:143], v[156:159], v[116:119]
	v_mfma_f32_16x16x32_bf16 v[112:115], v[148:151], v[156:159], v[112:115]
	v_mfma_f32_16x16x32_bf16 v[108:111], v[140:143], v[164:167], v[108:111]
	v_mfma_f32_16x16x32_bf16 v[104:107], v[148:151], v[164:167], v[104:107]
	v_mfma_f32_16x16x32_bf16 v[100:103], v[140:143], v[172:175], v[100:103]
	v_mfma_f32_16x16x32_bf16 v[96:99], v[148:151], v[172:175], v[96:99]
	v_mfma_f32_16x16x32_bf16 v[124:127], v[144:147], v[134:137], v[124:127]
	v_mfma_f32_16x16x32_bf16 v[180:183], v[152:155], v[134:137], v[120:123]
	v_mfma_f32_16x16x32_bf16 v[116:119], v[144:147], v[160:163], v[116:119]
	v_mfma_f32_16x16x32_bf16 v[184:187], v[152:155], v[160:163], v[112:115]
	v_mfma_f32_16x16x32_bf16 v[108:111], v[144:147], v[168:171], v[108:111]
	v_mfma_f32_16x16x32_bf16 v[188:191], v[152:155], v[168:171], v[104:107]
	v_mfma_f32_16x16x32_bf16 v[100:103], v[144:147], v[176:179], v[100:103]
	v_mfma_f32_16x16x32_bf16 v[192:195], v[152:155], v[176:179], v[96:99]
	s_barrier
	ds_read_b128 v[96:99], v226 offset:0
	ds_read_b128 v[104:107], v226 offset:0x400
	ds_read_b128 v[112:115], v226 offset:0x800
	ds_read_b128 v[120:123], v226 offset:0xc00
	s_barrier
; #define WAIT_V(n) asm volatile("s_waitcnt vmcnt(%0)" ::"n"(n) : "memory")
; #define SCHED() __builtin_amdgcn_sched_barrier(0)
; #define LGKM(n) asm volatile("s_waitcnt lgkmcnt(%0)" ::"n"(n) : "memory")
; #define LDA(b, h) do { const unsigned pa_ = lds0 + SLOTA(b, h) + wr * 8192 + laneoff; _Pragma("unroll") for (int m = 0; m < 4; ++m)   \
;       _Pragma("unroll") for (int k = 0; k < 2; ++k) DSR(At[m][k], pa_, m * 2048 + k * 1024); } while (0)
; #define LDB(dst, b, h) do { const unsigned pb_ = lds0 + SLOTB(b, h) + wc * 4096 + laneoff; _Pragma("unroll") for (int n = 0; n < 2; ++n) \
;       _Pragma("unroll") for (int k = 0; k < 2; ++k) DSR(dst[n][k], pb_, n * 2048 + k * 1024); } while (0)
; #define BAR __builtin_amdgcn_s_barrier()
; #define LGKM(n) asm volatile("s_waitcnt lgkmcnt(%0)" ::"n"(n) : "memory")
; template <int EPI, bool SWP> ...
;     ...
;     LDA(0, 1); WAIT_V(4); BAR; LGKM(0); SCHED(); MMA(1, 0, B0); MMA(1, 1, B1); BAR; SCHED(); }
;   { LDB(B0, 1, 0); LDA(1, 0); WAIT_V(2); BAR; LGKM(0); SCHED(); MMA(0, 0, B0); BAR; SCHED();
	s_waitcnt lgkmcnt(0)
	v_mfma_f32_16x16x32_bf16 v[92:95], v[96:99], v[130:133], v[92:95]
	v_mfma_f32_16x16x32_bf16 v[88:91], v[112:115], v[130:133], v[88:91]
	v_mfma_f32_16x16x32_bf16 v[84:87], v[96:99], v[156:159], v[84:87]
	v_mfma_f32_16x16x32_bf16 v[80:83], v[112:115], v[156:159], v[80:83]
	v_mfma_f32_16x16x32_bf16 v[76:79], v[96:99], v[164:167], v[76:79]
	v_mfma_f32_16x16x32_bf16 v[72:75], v[112:115], v[164:167], v[72:75]
	v_mfma_f32_16x16x32_bf16 v[68:71], v[96:99], v[172:175], v[68:71]
	v_mfma_f32_16x16x32_bf16 v[64:67], v[112:115], v[172:175], v[64:67]
	v_mfma_f32_16x16x32_bf16 v[92:95], v[104:107], v[134:137], v[92:95]
	v_mfma_f32_16x16x32_bf16 v[196:199], v[120:123], v[134:137], v[88:91]
	v_mfma_f32_16x16x32_bf16 v[84:87], v[104:107], v[160:163], v[84:87]
	v_mfma_f32_16x16x32_bf16 v[200:203], v[120:123], v[160:163], v[80:83]
	v_mfma_f32_16x16x32_bf16 v[76:79], v[104:107], v[168:171], v[76:79]
	v_mfma_f32_16x16x32_bf16 v[204:207], v[120:123], v[168:171], v[72:75]
	v_mfma_f32_16x16x32_bf16 v[68:71], v[104:107], v[176:179], v[68:71]
	v_mfma_f32_16x16x32_bf16 v[176:179], v[120:123], v[176:179], v[64:67]
	s_barrier
	ds_read_b128 v[64:67], v227 offset:0
	ds_read_b128 v[72:75], v227 offset:0x400
	ds_read_b128 v[80:83], v227 offset:0x800
	ds_read_b128 v[88:91], v227 offset:0xc00
	ds_read_b128 v[156:159], v227 offset:0x1000
	ds_read_b128 v[160:163], v227 offset:0x1400
	ds_read_b128 v[164:167], v227 offset:0x1800
	ds_read_b128 v[168:171], v227 offset:0x1c00
	s_waitcnt vmcnt(4)
	s_barrier
	s_waitcnt lgkmcnt(0)
	v_mfma_f32_16x16x32_bf16 v[60:63], v[140:143], v[64:67], v[60:63]
	v_mfma_f32_16x16x32_bf16 v[56:59], v[148:151], v[64:67], v[56:59]
	v_mfma_f32_16x16x32_bf16 v[52:55], v[140:143], v[80:83], v[52:55]
	v_mfma_f32_16x16x32_bf16 v[48:51], v[148:151], v[80:83], v[48:51]
	v_mfma_f32_16x16x32_bf16 v[44:47], v[140:143], v[156:159], v[44:47]
	v_mfma_f32_16x16x32_bf16 v[40:43], v[148:151], v[156:159], v[40:43]
	v_mfma_f32_16x16x32_bf16 v[36:39], v[140:143], v[164:167], v[36:39]
	v_mfma_f32_16x16x32_bf16 v[32:35], v[148:151], v[164:167], v[32:35]
	v_mfma_f32_16x16x32_bf16 v[60:63], v[144:147], v[72:75], v[60:63]
	v_mfma_f32_16x16x32_bf16 v[128:131], v[152:155], v[72:75], v[56:59]
	v_mfma_f32_16x16x32_bf16 v[52:55], v[144:147], v[88:91], v[52:55]
	v_mfma_f32_16x16x32_bf16 v[132:135], v[152:155], v[88:91], v[48:51]
	v_mfma_f32_16x16x32_bf16 v[44:47], v[144:147], v[160:163], v[44:47]
	v_mfma_f32_16x16x32_bf16 v[136:139], v[152:155], v[160:163], v[40:43]
	v_mfma_f32_16x16x32_bf16 v[36:39], v[144:147], v[168:171], v[36:39]
	v_mfma_f32_16x16x32_bf16 v[140:143], v[152:155], v[168:171], v[32:35]
	v_mfma_f32_16x16x32_bf16 v[28:31], v[96:99], v[64:67], v[28:31]
	v_mfma_f32_16x16x32_bf16 v[24:27], v[112:115], v[64:67], v[24:27]
	v_mfma_f32_16x16x32_bf16 v[20:23], v[96:99], v[80:83], v[20:23]
	v_mfma_f32_16x16x32_bf16 v[16:19], v[112:115], v[80:83], v[16:19]
	v_mfma_f32_16x16x32_bf16 v[12:15], v[96:99], v[156:159], v[12:15]
	v_mfma_f32_16x16x32_bf16 v[8:11], v[112:115], v[156:159], v[8:11]
	v_mfma_f32_16x16x32_bf16 v[4:7], v[96:99], v[164:167], v[4:7]
	v_mfma_f32_16x16x32_bf16 v[0:3], v[112:115], v[164:167], v[0:3]
	v_mfma_f32_16x16x32_bf16 v[28:31], v[104:107], v[72:75], v[28:31]
	v_mfma_f32_16x16x32_bf16 v[144:147], v[120:123], v[72:75], v[24:27]
	v_mfma_f32_16x16x32_bf16 v[20:23], v[104:107], v[88:91], v[20:23]
	v_mfma_f32_16x16x32_bf16 v[148:151], v[120:123], v[88:91], v[16:19]
	v_mfma_f32_16x16x32_bf16 v[12:15], v[104:107], v[160:163], v[12:15]
	v_mfma_f32_16x16x32_bf16 v[152:155], v[120:123], v[160:163], v[8:11]
	v_mfma_f32_16x16x32_bf16 v[4:7], v[104:107], v[168:171], v[4:7]
	v_mfma_f32_16x16x32_bf16 v[156:159], v[120:123], v[168:171], v[0:3]
	s_barrier
	ds_read_b128 v[0:3], v229 offset:0
	ds_read_b128 v[8:11], v229 offset:0x400
	ds_read_b128 v[16:19], v229 offset:0x800
	ds_read_b128 v[24:27], v229 offset:0xc00
	ds_read_b128 v[32:35], v230 offset:0
	ds_read_b128 v[40:43], v230 offset:0x400
	ds_read_b128 v[48:51], v230 offset:0x800
	ds_read_b128 v[56:59], v230 offset:0xc00
	ds_read_b128 v[64:67], v230 offset:0x1000
	ds_read_b128 v[220:223], v230 offset:0x1400
	ds_read_b128 v[238:241], v230 offset:0x1800
	ds_read_b128 v[242:245], v230 offset:0x1c00
	s_waitcnt vmcnt(2)
	s_barrier
; #define WAIT_V(n) asm volatile("s_waitcnt vmcnt(%0)" ::"n"(n) : "memory")
; #define SCHED() __builtin_amdgcn_sched_barrier(0)
; #define LGKM(n) asm volatile("s_waitcnt lgkmcnt(%0)" ::"n"(n) : "memory")
; #define STAGE_AX(AG, b, h, kt) do { _Pragma("unroll") for (int i = 0; i < 2; ++i)                                    \
;       __builtin_amdgcn_global_load_lds((const unsigned*)(((AG) + ((size_t)(kt) * (BK * 2) + (size_t)((h) * 2 + i) * 128 * lda)) + aoff), \
;                                        (unsigned*)(shm + SLOTA(b, h) + wid * 1024 + i * 8192), 16, 0, 0); } while (0)
; #define STAGE_BX(BG, b, h, kt) do { _Pragma("unroll") for (int i = 0; i < 2; ++i)                                    \
;       __builtin_amdgcn_global_load_lds((const unsigned*)(((BG) + ((size_t)(kt) * (BK * 2) + (size_t)((h) * 2 + i) * 128 * K)) + boff),   \
;                                        (unsigned*)(shm + SLOTB(b, h) + wid * 1024 + i * 8192), 16, 0, 0); } while (0)
; #define LDA(b, h) do { const unsigned pa_ = lds0 + SLOTA(b, h) + wr * 8192 + laneoff; _Pragma("unroll") for (int m = 0; m < 4; ++m)   \
;       _Pragma("unroll") for (int k = 0; k < 2; ++k) DSR(At[m][k], pa_, m * 2048 + k * 1024); } while (0)
; #define LDB(dst, b, h) do { const unsigned pb_ = lds0 + SLOTB(b, h) + wc * 4096 + laneoff; _Pragma("unroll") for (int n = 0; n < 2; ++n) \
;       _Pragma("unroll") for (int k = 0; k < 2; ++k) DSR(dst[n][k], pb_, n * 2048 + k * 1024); } while (0)
; #define BAR __builtin_amdgcn_s_barrier()
; #define LGKM(n) asm volatile("s_waitcnt lgkmcnt(%0)" ::"n"(n) : "memory")
; template <int EPI, bool SWP> ...
;     ...
;   { LDB(B0, 1, 0); LDA(1, 0); WAIT_V(2); BAR; LGKM(0); SCHED(); MMA(0, 0, B0); BAR; SCHED();
;     LDB(B1, 1, 1); WAIT_V(0); BAR; LGKM(0); SCHED(); MMA(0, 1, B1); BAR; SCHED();
;     LDA(1, 1);
;     if (has_next) { STAGE_BX(Bg_n, 0, 0, 0); STAGE_AX(Ag_n, 0, 0, 0); STAGE_BX(Bg_n, 0, 1, 0); STAGE_AX(Ag_n, 0, 1, 0); }
;     BAR; LGKM(0); SCHED(); MMA(1, 0, B0); MMA(1, 1, B1); BAR; SCHED(); }
;   if (wr == 0) BAR;
;   if (has_next) {
;     STAGE_BX(Bg_n, 1, 0, 1); STAGE_AX(Ag_n, 1, 0, 1); STAGE_BX(Bg_n, 1, 1, 1);
;     if (e.nss > 0 && tid < 256) s_rstd_n[tid] = rsqrtf(ss_next * (1.f / DM) + 1e-6f);
	s_waitcnt lgkmcnt(0)
	v_mfma_f32_16x16x32_bf16 v[72:75], v[0:3], v[32:35], v[124:127]
	v_mfma_f32_16x16x32_bf16 v[120:123], v[8:11], v[40:43], v[72:75]
	v_mfma_f32_16x16x32_bf16 v[72:75], v[16:19], v[32:35], v[180:183]
	v_mfma_f32_16x16x32_bf16 v[124:127], v[24:27], v[40:43], v[72:75]
	v_mfma_f32_16x16x32_bf16 v[72:75], v[0:3], v[48:51], v[116:119]
	v_mfma_f32_16x16x32_bf16 v[112:115], v[8:11], v[56:59], v[72:75]
	v_mfma_f32_16x16x32_bf16 v[72:75], v[16:19], v[48:51], v[184:187]
	v_mfma_f32_16x16x32_bf16 v[116:119], v[24:27], v[56:59], v[72:75]
	v_mfma_f32_16x16x32_bf16 v[72:75], v[0:3], v[64:67], v[108:111]
	v_mfma_f32_16x16x32_bf16 v[104:107], v[8:11], v[220:223], v[72:75]
	v_mfma_f32_16x16x32_bf16 v[72:75], v[16:19], v[64:67], v[188:191]
	v_mfma_f32_16x16x32_bf16 v[108:111], v[24:27], v[220:223], v[72:75]
	v_mfma_f32_16x16x32_bf16 v[72:75], v[0:3], v[238:241], v[100:103]
	v_mfma_f32_16x16x32_bf16 v[96:99], v[8:11], v[242:245], v[72:75]
	v_mfma_f32_16x16x32_bf16 v[72:75], v[16:19], v[238:241], v[192:195]
	v_mfma_f32_16x16x32_bf16 v[100:103], v[24:27], v[242:245], v[72:75]
	s_barrier
	ds_read_b128 v[160:163], v231 offset:0
	ds_read_b128 v[164:167], v231 offset:0x400
	ds_read_b128 v[168:171], v231 offset:0x800
	ds_read_b128 v[172:175], v231 offset:0xc00
	s_waitcnt vmcnt(0)
	s_barrier
	s_waitcnt lgkmcnt(0)
	v_mfma_f32_16x16x32_bf16 v[72:75], v[160:163], v[32:35], v[92:95]
	v_mfma_f32_16x16x32_bf16 v[32:35], v[168:171], v[32:35], v[196:199]
	v_mfma_f32_16x16x32_bf16 v[92:95], v[172:175], v[40:43], v[32:35]
	v_mfma_f32_16x16x32_bf16 v[32:35], v[160:163], v[48:51], v[84:87]
	v_mfma_f32_16x16x32_bf16 v[80:83], v[164:167], v[56:59], v[32:35]
	v_mfma_f32_16x16x32_bf16 v[32:35], v[168:171], v[48:51], v[200:203]
	v_mfma_f32_16x16x32_bf16 v[84:87], v[172:175], v[56:59], v[32:35]
	v_mfma_f32_16x16x32_bf16 v[32:35], v[160:163], v[64:67], v[76:79]
	v_mfma_f32_16x16x32_bf16 v[88:91], v[164:167], v[40:43], v[72:75]
	v_mfma_f32_16x16x32_bf16 v[72:75], v[164:167], v[220:223], v[32:35]
	v_mfma_f32_16x16x32_bf16 v[32:35], v[168:171], v[64:67], v[204:207]
	v_mfma_f32_16x16x32_bf16 v[76:79], v[172:175], v[220:223], v[32:35]
	v_mfma_f32_16x16x32_bf16 v[32:35], v[160:163], v[238:241], v[68:71]
	v_mfma_f32_16x16x32_bf16 v[64:67], v[164:167], v[242:245], v[32:35]
	v_mfma_f32_16x16x32_bf16 v[32:35], v[168:171], v[238:241], v[176:179]
	v_mfma_f32_16x16x32_bf16 v[68:71], v[172:175], v[242:245], v[32:35]
	s_barrier
	ds_read_b128 v[200:203], v232 offset:0
	ds_read_b128 v[204:207], v232 offset:0x400
	ds_read_b128 v[192:195], v232 offset:0x800
	ds_read_b128 v[196:199], v232 offset:0xc00
	ds_read_b128 v[184:187], v232 offset:0x1000
	ds_read_b128 v[188:191], v232 offset:0x1400
	ds_read_b128 v[176:179], v232 offset:0x1800
	ds_read_b128 v[180:183], v232 offset:0x1c00
	s_and_b64 vcc, exec, s[44:45]
	v_lshl_add_u64 v[220:221], s[50:51], 0, v[208:209]
	v_lshl_add_u64 v[222:223], s[48:49], 0, v[208:209]
	s_cbranch_vccz .LBB0_388
	s_mov_b32 m0, s16
	v_lshl_add_u64 v[32:33], v[220:221], 0, s[4:5]
	global_load_lds_dwordx4 v[220:221], off
	s_mov_b32 m0, s17
	s_nop 0
	global_load_lds_dwordx4 v[32:33], off
	s_mov_b32 m0, s3
	v_lshl_add_u64 v[32:33], v[222:223], 0, s[4:5]
	global_load_lds_dwordx4 v[222:223], off
	s_mov_b32 m0, s18
	s_nop 0
	global_load_lds_dwordx4 v[32:33], off
	v_lshl_add_u64 v[32:33], v[220:221], 0, s[8:9]
	s_mov_b32 m0, s19
	s_nop 0
	global_load_lds_dwordx4 v[32:33], off
	v_lshl_add_u64 v[32:33], v[220:221], 0, s[10:11]
	s_mov_b32 m0, s60
	s_nop 0
	global_load_lds_dwordx4 v[32:33], off
	v_lshl_add_u64 v[32:33], v[222:223], 0, s[8:9]
	s_mov_b32 m0, s61
	s_nop 0
	global_load_lds_dwordx4 v[32:33], off
	v_lshl_add_u64 v[32:33], v[222:223], 0, s[10:11]
	s_mov_b32 m0, s62
	s_nop 0
	global_load_lds_dwordx4 v[32:33], off
